# back-edge rotation variant: s_setprio 0 first, then the counter / pointer updates, then the loop-closing barrier
# speedup vs baseline: 1.0001x; 1.0001x over previous
; #define PG8_STAGE(bufoff, gbase, voff) do { _Pragma("unroll") for (int _i = 0; _i < 2; ++_i) \
;         __builtin_amdgcn_global_load_lds((const unsigned*)((const char*)(gbase) + (voff)[_i]), (PG8_LAS unsigned*)(lds + (bufoff) + ldsw + _i * 8192), 16, 0, 0); } while (0)
; #define PG8_LDA(dst, b, h) do { _Pragma("unroll") for (int m = 0; m < 4; ++m) _Pragma("unroll") for (int k = 0; k < 2; ++k) dst[m][k] = *(const PG8_LAS bf16x8*)(lds + PG8_SA(b, h) + aoff + m * 2048 + k * 1024); } while (0)
; #define PG8_LDB(dst, b, h) do { _Pragma("unroll") for (int n = 0; n < 2; ++n) _Pragma("unroll") for (int k = 0; k < 2; ++k) dst[n][k] = *(const PG8_LAS bf16x8*)(lds + PG8_SB(b, h) + boff + n * 2048 + k * 1024); } while (0)
; #define PG8_MMA(ai, bj, At, Bt) do { __builtin_amdgcn_s_setprio(1); _Pragma("unroll") for (int m = 0; m < 4; ++m) _Pragma("unroll") for (int n = 0; n < 2; ++n) _Pragma("unroll") for (int k = 0; k < 2; ++k) \
;         acc[ai][bj][m][n] = __builtin_amdgcn_mfma_f32_16x16x32_bf16(Bt[n][k], At[m][k], acc[ai][bj][m][n], 0, 0, 0); __builtin_amdgcn_s_setprio(0); } while (0)
; #define PG8_WAIT_V(n) asm volatile("s_waitcnt vmcnt(" #n ")" ::: "memory")
; #define PG8_WAIT_L(n) asm volatile("s_waitcnt lgkmcnt(" #n ")" ::: "memory")
; #define PG8_BAR __builtin_amdgcn_s_barrier()
; template <class Epi, class Sched, bool ALIGN_EPI = false, bool SP2 = false>
; __device__ __forceinline__ void gemm_phase(PG8_LAS unsigned char* lds, const Gemm g, const Sched& S, const Epi& E) {
;     ...
;             const char* a1 = cA + (size_t)(t + 1) * kstep;
;             const char* a2 = last ? nA : cA + (size_t)(t + 2) * kstep; const char* b2 = last ? nB : cB + (size_t)(t + 2) * kstep;
;             const char* a3 = a2 + kstep; const char* b3 = b2 + kstep;
;             if (last && has_next) S.a_ready(nxt);
;             if constexpr (SP2) {
;             PG8_LDB(B0, 0, 0); PG8_LDB(B1, 0, 1); PG8_SCHED; PG8_LDA(At, 0, 0); PG8_STAGE(PG8_SA(1, 1), a1 + hstepA, voffA);
;             PG8_WAIT_V(8); PG8_WAIT_L(0); PG8_BAR; PG8_MMA(0, 0, At, B0); PG8_MMA(0, 1, At, B1); PG8_BAR; PG8_SCHED;
;             PG8_LDA(At, 0, 1); PG8_STAGE(PG8_SB(0, 0), b2, voffB); PG8_STAGE(PG8_SB(0, 1), b2 + hstepB, voffB); PG8_STAGE(PG8_SA(0, 0), a2, voffA);
;             PG8_WAIT_V(8); PG8_WAIT_L(0); PG8_BAR; PG8_MMA(1, 0, At, B0); PG8_MMA(1, 1, At, B1); PG8_BAR; PG8_SCHED;
.LBB0_157:
	v_add_u32_e32 v136, s2, v139
	ds_read_b128 v[186:189], v136
	ds_read_b128 v[190:193], v136 offset:1024
	ds_read_b128 v[194:197], v136 offset:2048
	ds_read_b128 v[198:201], v136 offset:3072
	v_add_u32_e32 v136, s3, v139
	ds_read_b128 v[202:205], v136
	ds_read_b128 v[206:209], v136 offset:1024
	ds_read_b128 v[210:213], v136 offset:2048
	ds_read_b128 v[214:217], v136 offset:3072
	s_add_u32 s38, s36, 0xfffc0080
	s_addc_u32 s39, s37, -1
	s_cmp_eq_u32 s45, 12
	s_cselect_b32 s41, s7, s39
	s_cselect_b32 s40, s29, s38
	s_cselect_b32 s39, s27, s44
	s_cselect_b32 s38, s42, s43
	v_lshl_add_u64 v[250:251], s[36:37], 0, v[178:179]
	s_add_i32 m0, s63, 0xc000
	ds_read_b128 v[218:221], v159
	ds_read_b128 v[222:225], v159 offset:1024
	ds_read_b128 v[226:229], v159 offset:2048
	ds_read_b128 v[230:233], v159 offset:3072
	ds_read_b128 v[234:237], v159 offset:4096
	ds_read_b128 v[238:241], v159 offset:5120
	ds_read_b128 v[242:245], v159 offset:6144
	ds_read_b128 v[246:249], v159 offset:7168
	global_load_lds_dwordx4 v[250:251], off
	v_lshl_add_u64 v[250:251], s[36:37], 0, v[180:181]
	s_add_i32 m0, s63, 0xe000
	s_nop 0
	global_load_lds_dwordx4 v[250:251], off
	s_waitcnt vmcnt(8)
	s_waitcnt lgkmcnt(0)
	s_barrier
	s_setprio 1
	s_waitcnt lgkmcnt(0)
	v_mfma_f32_16x16x32_bf16 v[124:127], v[186:189], v[218:221], v[124:127]
	v_mfma_f32_16x16x32_bf16 v[120:123], v[194:197], v[218:221], v[120:123]
	v_mfma_f32_16x16x32_bf16 v[108:111], v[186:189], v[226:229], v[108:111]
	v_mfma_f32_16x16x32_bf16 v[104:107], v[194:197], v[226:229], v[104:107]
	v_mfma_f32_16x16x32_bf16 v[92:95], v[186:189], v[234:237], v[92:95]
	v_mfma_f32_16x16x32_bf16 v[88:91], v[194:197], v[234:237], v[88:91]
	v_mfma_f32_16x16x32_bf16 v[76:79], v[186:189], v[242:245], v[76:79]
	v_mfma_f32_16x16x32_bf16 v[72:75], v[194:197], v[242:245], v[72:75]
	v_mfma_f32_16x16x32_bf16 v[124:127], v[190:193], v[222:225], v[124:127]
	v_mfma_f32_16x16x32_bf16 v[120:123], v[198:201], v[222:225], v[120:123]
	v_mfma_f32_16x16x32_bf16 v[108:111], v[190:193], v[230:233], v[108:111]
	v_mfma_f32_16x16x32_bf16 v[104:107], v[198:201], v[230:233], v[104:107]
	v_mfma_f32_16x16x32_bf16 v[92:95], v[190:193], v[238:241], v[92:95]
	v_mfma_f32_16x16x32_bf16 v[88:91], v[198:201], v[238:241], v[88:91]
	v_mfma_f32_16x16x32_bf16 v[76:79], v[190:193], v[246:249], v[76:79]
	v_mfma_f32_16x16x32_bf16 v[72:75], v[198:201], v[246:249], v[72:75]
	s_setprio 0
	s_setprio 1
	v_mfma_f32_16x16x32_bf16 v[116:119], v[202:205], v[218:221], v[116:119]
	v_mfma_f32_16x16x32_bf16 v[112:115], v[210:213], v[218:221], v[112:115]
	v_mfma_f32_16x16x32_bf16 v[100:103], v[202:205], v[226:229], v[100:103]
	v_mfma_f32_16x16x32_bf16 v[96:99], v[210:213], v[226:229], v[96:99]
	v_mfma_f32_16x16x32_bf16 v[84:87], v[202:205], v[234:237], v[84:87]
	v_mfma_f32_16x16x32_bf16 v[80:83], v[210:213], v[234:237], v[80:83]
	v_mfma_f32_16x16x32_bf16 v[68:71], v[202:205], v[242:245], v[68:71]
	v_mfma_f32_16x16x32_bf16 v[64:67], v[210:213], v[242:245], v[64:67]
	v_mfma_f32_16x16x32_bf16 v[116:119], v[206:209], v[222:225], v[116:119]
	v_mfma_f32_16x16x32_bf16 v[112:115], v[214:217], v[222:225], v[112:115]
	v_mfma_f32_16x16x32_bf16 v[100:103], v[206:209], v[230:233], v[100:103]
	v_mfma_f32_16x16x32_bf16 v[96:99], v[214:217], v[230:233], v[96:99]
	v_mfma_f32_16x16x32_bf16 v[84:87], v[206:209], v[238:241], v[84:87]
	v_mfma_f32_16x16x32_bf16 v[80:83], v[214:217], v[238:241], v[80:83]
	v_mfma_f32_16x16x32_bf16 v[68:71], v[206:209], v[246:249], v[68:71]
	v_mfma_f32_16x16x32_bf16 v[64:67], v[214:217], v[246:249], v[64:67]
	s_setprio 0
	s_barrier
	s_add_i32 s46, s2, s62
	v_lshl_add_u64 v[250:251], s[38:39], 0, v[130:131]
	s_mov_b32 m0, s46
	ds_read_b128 v[218:221], v159 offset:16384
	ds_read_b128 v[222:225], v159 offset:17408
	ds_read_b128 v[226:229], v159 offset:18432
	ds_read_b128 v[230:233], v159 offset:19456
	ds_read_b128 v[234:237], v159 offset:20480
	ds_read_b128 v[238:241], v159 offset:21504
	ds_read_b128 v[242:245], v159 offset:22528
	ds_read_b128 v[246:249], v159 offset:23552
	global_load_lds_dwordx4 v[250:251], off
	s_add_i32 m0, s46, 0x2000
	s_add_u32 s46, s38, 0x40000
	v_lshl_add_u64 v[252:253], s[38:39], 0, v[134:135]
	s_addc_u32 s47, s39, 0
	s_add_i32 s48, s3, s62
	global_load_lds_dwordx4 v[252:253], off
	v_lshl_add_u64 v[166:167], s[46:47], 0, v[130:131]
	s_mov_b32 m0, s48
	v_lshl_add_u64 v[168:169], s[40:41], 0, v[132:133]
	global_load_lds_dwordx4 v[166:167], off
	v_lshl_add_u64 v[166:167], s[46:47], 0, v[134:135]
	s_add_i32 m0, s48, 0x2000
	s_nop 0
	global_load_lds_dwordx4 v[166:167], off
	v_lshl_add_u64 v[166:167], s[40:41], 0, v[128:129]
	s_mov_b32 m0, s63
	s_nop 0
	global_load_lds_dwordx4 v[166:167], off
	s_mov_b32 m0, s64
	s_nop 0
	global_load_lds_dwordx4 v[168:169], off
	s_waitcnt vmcnt(8)
	s_waitcnt lgkmcnt(0)
	s_barrier
; #define PG8_STAGE(bufoff, gbase, voff) do { _Pragma("unroll") for (int _i = 0; _i < 2; ++_i) \
;         __builtin_amdgcn_global_load_lds((const unsigned*)((const char*)(gbase) + (voff)[_i]), (PG8_LAS unsigned*)(lds + (bufoff) + ldsw + _i * 8192), 16, 0, 0); } while (0)
; #define PG8_LDA(dst, b, h) do { _Pragma("unroll") for (int m = 0; m < 4; ++m) _Pragma("unroll") for (int k = 0; k < 2; ++k) dst[m][k] = *(const PG8_LAS bf16x8*)(lds + PG8_SA(b, h) + aoff + m * 2048 + k * 1024); } while (0)
; #define PG8_LDB(dst, b, h) do { _Pragma("unroll") for (int n = 0; n < 2; ++n) _Pragma("unroll") for (int k = 0; k < 2; ++k) dst[n][k] = *(const PG8_LAS bf16x8*)(lds + PG8_SB(b, h) + boff + n * 2048 + k * 1024); } while (0)
; #define PG8_MMA(ai, bj, At, Bt) do { __builtin_amdgcn_s_setprio(1); _Pragma("unroll") for (int m = 0; m < 4; ++m) _Pragma("unroll") for (int n = 0; n < 2; ++n) _Pragma("unroll") for (int k = 0; k < 2; ++k) \
;         acc[ai][bj][m][n] = __builtin_amdgcn_mfma_f32_16x16x32_bf16(Bt[n][k], At[m][k], acc[ai][bj][m][n], 0, 0, 0); __builtin_amdgcn_s_setprio(0); } while (0)
; #define PG8_WAIT_V(n) asm volatile("s_waitcnt vmcnt(" #n ")" ::: "memory")
; #define PG8_WAIT_L(n) asm volatile("s_waitcnt lgkmcnt(" #n ")" ::: "memory")
; #define PG8_BAR __builtin_amdgcn_s_barrier()
; #define PG8_SCHED __builtin_amdgcn_sched_barrier(0)
; template <class Epi, class Sched, bool ALIGN_EPI = false, bool SP2 = false>
; __device__ __forceinline__ void gemm_phase(PG8_LAS unsigned char* lds, const Gemm g, const Sched& S, const Epi& E) {
;     ...
;             PG8_WAIT_V(8); PG8_WAIT_L(0); PG8_BAR; PG8_MMA(1, 0, At, B0); PG8_MMA(1, 1, At, B1); PG8_BAR; PG8_SCHED;
;             PG8_LDB(B0, 1, 0); PG8_LDB(B1, 1, 1); PG8_SCHED; PG8_LDA(At, 1, 0); PG8_STAGE(PG8_SA(0, 1), a2 + hstepA, voffA);
;             PG8_WAIT_V(8); PG8_WAIT_L(0); PG8_BAR; PG8_MMA(0, 0, At, B0); PG8_MMA(0, 1, At, B1); PG8_BAR; PG8_SCHED;
	s_setprio 1
	s_waitcnt lgkmcnt(0)
	v_mfma_f32_16x16x32_bf16 v[60:63], v[186:189], v[218:221], v[60:63]
	v_mfma_f32_16x16x32_bf16 v[56:59], v[194:197], v[218:221], v[56:59]
	v_mfma_f32_16x16x32_bf16 v[44:47], v[186:189], v[226:229], v[44:47]
	v_mfma_f32_16x16x32_bf16 v[40:43], v[194:197], v[226:229], v[40:43]
	v_mfma_f32_16x16x32_bf16 v[28:31], v[186:189], v[234:237], v[28:31]
	v_mfma_f32_16x16x32_bf16 v[24:27], v[194:197], v[234:237], v[24:27]
	v_mfma_f32_16x16x32_bf16 v[12:15], v[186:189], v[242:245], v[12:15]
	v_mfma_f32_16x16x32_bf16 v[8:11], v[194:197], v[242:245], v[8:11]
	v_mfma_f32_16x16x32_bf16 v[60:63], v[190:193], v[222:225], v[60:63]
	v_mfma_f32_16x16x32_bf16 v[56:59], v[198:201], v[222:225], v[56:59]
	v_mfma_f32_16x16x32_bf16 v[44:47], v[190:193], v[230:233], v[44:47]
	v_mfma_f32_16x16x32_bf16 v[40:43], v[198:201], v[230:233], v[40:43]
	v_mfma_f32_16x16x32_bf16 v[28:31], v[190:193], v[238:241], v[28:31]
	v_mfma_f32_16x16x32_bf16 v[24:27], v[198:201], v[238:241], v[24:27]
	v_mfma_f32_16x16x32_bf16 v[12:15], v[190:193], v[246:249], v[12:15]
	v_mfma_f32_16x16x32_bf16 v[8:11], v[198:201], v[246:249], v[8:11]
	s_setprio 0
	s_setprio 1
	v_mfma_f32_16x16x32_bf16 v[52:55], v[202:205], v[218:221], v[52:55]
	v_mfma_f32_16x16x32_bf16 v[48:51], v[210:213], v[218:221], v[48:51]
	v_mfma_f32_16x16x32_bf16 v[36:39], v[202:205], v[226:229], v[36:39]
	v_mfma_f32_16x16x32_bf16 v[32:35], v[210:213], v[226:229], v[32:35]
	v_mfma_f32_16x16x32_bf16 v[20:23], v[202:205], v[234:237], v[20:23]
	v_mfma_f32_16x16x32_bf16 v[16:19], v[210:213], v[234:237], v[16:19]
	v_mfma_f32_16x16x32_bf16 v[4:7], v[202:205], v[242:245], v[4:7]
	v_mfma_f32_16x16x32_bf16 v[0:3], v[210:213], v[242:245], v[0:3]
	v_mfma_f32_16x16x32_bf16 v[52:55], v[206:209], v[222:225], v[52:55]
	v_mfma_f32_16x16x32_bf16 v[48:51], v[214:217], v[222:225], v[48:51]
	v_mfma_f32_16x16x32_bf16 v[36:39], v[206:209], v[230:233], v[36:39]
	v_mfma_f32_16x16x32_bf16 v[32:35], v[214:217], v[230:233], v[32:35]
	v_mfma_f32_16x16x32_bf16 v[20:23], v[206:209], v[238:241], v[20:23]
	v_mfma_f32_16x16x32_bf16 v[16:19], v[214:217], v[238:241], v[16:19]
	v_mfma_f32_16x16x32_bf16 v[4:7], v[206:209], v[246:249], v[4:7]
	v_mfma_f32_16x16x32_bf16 v[0:3], v[214:217], v[246:249], v[0:3]
	s_setprio 0
	s_barrier
	s_add_i32 s46, 0, 0x18000
	v_add_u32_e32 v136, s46, v139
	s_add_i32 s47, 0, 0x1c000
	ds_read_b128 v[186:189], v136
	ds_read_b128 v[190:193], v136 offset:1024
	ds_read_b128 v[194:197], v136 offset:2048
	ds_read_b128 v[198:201], v136 offset:3072
	v_add_u32_e32 v136, s47, v139
	ds_read_b128 v[202:205], v136
	ds_read_b128 v[206:209], v136 offset:1024
	ds_read_b128 v[210:213], v136 offset:2048
	ds_read_b128 v[214:217], v136 offset:3072
	s_add_u32 s40, s40, 0x40000
	s_addc_u32 s41, s41, 0
	s_mov_b32 m0, s65
	v_lshl_add_u64 v[170:171], s[40:41], 0, v[128:129]
	ds_read_b128 v[218:221], v159 offset:32768
	ds_read_b128 v[222:225], v159 offset:33792
	ds_read_b128 v[226:229], v159 offset:34816
	ds_read_b128 v[230:233], v159 offset:35840
	ds_read_b128 v[234:237], v159 offset:36864
	ds_read_b128 v[238:241], v159 offset:37888
	ds_read_b128 v[242:245], v159 offset:38912
	ds_read_b128 v[246:249], v159 offset:39936
	global_load_lds_dwordx4 v[170:171], off
	v_lshl_add_u64 v[170:171], s[40:41], 0, v[132:133]
	s_mov_b32 m0, s66
	s_nop 0
	global_load_lds_dwordx4 v[170:171], off
	s_waitcnt vmcnt(8)
	s_waitcnt lgkmcnt(0)
	s_barrier
	s_setprio 1
	s_waitcnt lgkmcnt(0)
	v_mfma_f32_16x16x32_bf16 v[124:127], v[186:189], v[218:221], v[124:127]
	v_mfma_f32_16x16x32_bf16 v[120:123], v[194:197], v[218:221], v[120:123]
	v_mfma_f32_16x16x32_bf16 v[108:111], v[186:189], v[226:229], v[108:111]
	v_mfma_f32_16x16x32_bf16 v[104:107], v[194:197], v[226:229], v[104:107]
	v_mfma_f32_16x16x32_bf16 v[92:95], v[186:189], v[234:237], v[92:95]
	v_mfma_f32_16x16x32_bf16 v[88:91], v[194:197], v[234:237], v[88:91]
	v_mfma_f32_16x16x32_bf16 v[76:79], v[186:189], v[242:245], v[76:79]
	v_mfma_f32_16x16x32_bf16 v[72:75], v[194:197], v[242:245], v[72:75]
	v_mfma_f32_16x16x32_bf16 v[124:127], v[190:193], v[222:225], v[124:127]
	v_mfma_f32_16x16x32_bf16 v[120:123], v[198:201], v[222:225], v[120:123]
	v_mfma_f32_16x16x32_bf16 v[108:111], v[190:193], v[230:233], v[108:111]
	v_mfma_f32_16x16x32_bf16 v[104:107], v[198:201], v[230:233], v[104:107]
	v_mfma_f32_16x16x32_bf16 v[92:95], v[190:193], v[238:241], v[92:95]
	v_mfma_f32_16x16x32_bf16 v[88:91], v[198:201], v[238:241], v[88:91]
	v_mfma_f32_16x16x32_bf16 v[76:79], v[190:193], v[246:249], v[76:79]
	v_mfma_f32_16x16x32_bf16 v[72:75], v[198:201], v[246:249], v[72:75]
	s_setprio 0
	s_setprio 1
	v_mfma_f32_16x16x32_bf16 v[116:119], v[202:205], v[218:221], v[116:119]
	v_mfma_f32_16x16x32_bf16 v[112:115], v[210:213], v[218:221], v[112:115]
	v_mfma_f32_16x16x32_bf16 v[100:103], v[202:205], v[226:229], v[100:103]
	v_mfma_f32_16x16x32_bf16 v[96:99], v[210:213], v[226:229], v[96:99]
	v_mfma_f32_16x16x32_bf16 v[84:87], v[202:205], v[234:237], v[84:87]
	v_mfma_f32_16x16x32_bf16 v[80:83], v[210:213], v[234:237], v[80:83]
	v_mfma_f32_16x16x32_bf16 v[68:71], v[202:205], v[242:245], v[68:71]
	v_mfma_f32_16x16x32_bf16 v[64:67], v[210:213], v[242:245], v[64:67]
	v_mfma_f32_16x16x32_bf16 v[116:119], v[206:209], v[222:225], v[116:119]
	v_mfma_f32_16x16x32_bf16 v[112:115], v[214:217], v[222:225], v[112:115]
	v_mfma_f32_16x16x32_bf16 v[100:103], v[206:209], v[230:233], v[100:103]
	v_mfma_f32_16x16x32_bf16 v[96:99], v[214:217], v[230:233], v[96:99]
	v_mfma_f32_16x16x32_bf16 v[84:87], v[206:209], v[238:241], v[84:87]
	v_mfma_f32_16x16x32_bf16 v[80:83], v[214:217], v[238:241], v[80:83]
	v_mfma_f32_16x16x32_bf16 v[68:71], v[206:209], v[246:249], v[68:71]
	v_mfma_f32_16x16x32_bf16 v[64:67], v[214:217], v[246:249], v[64:67]
	s_setprio 0
	s_barrier
; #define PG8_STAGE(bufoff, gbase, voff) do { _Pragma("unroll") for (int _i = 0; _i < 2; ++_i) \
;         __builtin_amdgcn_global_load_lds((const unsigned*)((const char*)(gbase) + (voff)[_i]), (PG8_LAS unsigned*)(lds + (bufoff) + ldsw + _i * 8192), 16, 0, 0); } while (0)
; #define PG8_LDA(dst, b, h) do { _Pragma("unroll") for (int m = 0; m < 4; ++m) _Pragma("unroll") for (int k = 0; k < 2; ++k) dst[m][k] = *(const PG8_LAS bf16x8*)(lds + PG8_SA(b, h) + aoff + m * 2048 + k * 1024); } while (0)
; #define PG8_MMA(ai, bj, At, Bt) do { __builtin_amdgcn_s_setprio(1); _Pragma("unroll") for (int m = 0; m < 4; ++m) _Pragma("unroll") for (int n = 0; n < 2; ++n) _Pragma("unroll") for (int k = 0; k < 2; ++k) \
;         acc[ai][bj][m][n] = __builtin_amdgcn_mfma_f32_16x16x32_bf16(Bt[n][k], At[m][k], acc[ai][bj][m][n], 0, 0, 0); __builtin_amdgcn_s_setprio(0); } while (0)
; #define PG8_WAIT_V(n) asm volatile("s_waitcnt vmcnt(" #n ")" ::: "memory")
; #define PG8_WAIT_L(n) asm volatile("s_waitcnt lgkmcnt(" #n ")" ::: "memory")
; #define PG8_BAR __builtin_amdgcn_s_barrier()
; #define PG8_SCHED __builtin_amdgcn_sched_barrier(0)
; template <class Epi, class Sched, bool ALIGN_EPI = false, bool SP2 = false>
; __device__ __forceinline__ void gemm_phase(PG8_LAS unsigned char* lds, const Gemm g, const Sched& S, const Epi& E) {
;     ...
;         for (int t = 0; t < nt; t += 2) {
;     ...
;             PG8_LDA(At, 1, 1); PG8_STAGE(PG8_SB(1, 0), b3, voffB); PG8_STAGE(PG8_SB(1, 1), b3 + hstepB, voffB); PG8_STAGE(PG8_SA(1, 0), a3, voffA);
;             PG8_WAIT_V(8); PG8_WAIT_L(0); PG8_BAR; PG8_MMA(1, 0, At, B0); PG8_MMA(1, 1, At, B1); PG8_BAR; PG8_SCHED;
	s_add_i32 s40, s46, s62
	v_lshl_add_u64 v[170:171], v[250:251], 0, s[22:23]
	s_mov_b32 m0, s40
	ds_read_b128 v[218:221], v159 offset:49152
	ds_read_b128 v[222:225], v159 offset:50176
	ds_read_b128 v[226:229], v159 offset:51200
	ds_read_b128 v[230:233], v159 offset:52224
	ds_read_b128 v[234:237], v159 offset:53248
	ds_read_b128 v[238:241], v159 offset:54272
	ds_read_b128 v[242:245], v159 offset:55296
	ds_read_b128 v[246:249], v159 offset:56320
	global_load_lds_dwordx4 v[170:171], off
	s_add_i32 m0, s40, 0x2000
	s_add_u32 s38, s38, 0x40080
	v_lshl_add_u64 v[170:171], v[252:253], 0, s[22:23]
	s_addc_u32 s39, s39, 0
	s_add_i32 s40, s47, s62
	global_load_lds_dwordx4 v[170:171], off
	v_lshl_add_u64 v[170:171], s[38:39], 0, v[130:131]
	s_mov_b32 m0, s40
	v_lshl_add_u64 v[166:167], v[166:167], 0, s[22:23]
	global_load_lds_dwordx4 v[170:171], off
	v_lshl_add_u64 v[170:171], s[38:39], 0, v[134:135]
	s_add_i32 m0, s40, 0x2000
	s_nop 0
	global_load_lds_dwordx4 v[170:171], off
	s_mov_b32 m0, s93
	s_nop 0
	global_load_lds_dwordx4 v[166:167], off
	v_lshl_add_u64 v[166:167], v[168:169], 0, s[22:23]
	s_mov_b32 m0, s96
	s_nop 0
	global_load_lds_dwordx4 v[166:167], off
	s_waitcnt vmcnt(8)
	s_waitcnt lgkmcnt(0)
	s_barrier
	s_setprio 1
	s_waitcnt lgkmcnt(0)
	v_mfma_f32_16x16x32_bf16 v[60:63], v[186:189], v[218:221], v[60:63]
	v_mfma_f32_16x16x32_bf16 v[56:59], v[194:197], v[218:221], v[56:59]
	v_mfma_f32_16x16x32_bf16 v[44:47], v[186:189], v[226:229], v[44:47]
	v_mfma_f32_16x16x32_bf16 v[40:43], v[194:197], v[226:229], v[40:43]
	v_mfma_f32_16x16x32_bf16 v[28:31], v[186:189], v[234:237], v[28:31]
	v_mfma_f32_16x16x32_bf16 v[24:27], v[194:197], v[234:237], v[24:27]
	v_mfma_f32_16x16x32_bf16 v[12:15], v[186:189], v[242:245], v[12:15]
	v_mfma_f32_16x16x32_bf16 v[8:11], v[194:197], v[242:245], v[8:11]
	v_mfma_f32_16x16x32_bf16 v[60:63], v[190:193], v[222:225], v[60:63]
	v_mfma_f32_16x16x32_bf16 v[56:59], v[198:201], v[222:225], v[56:59]
	v_mfma_f32_16x16x32_bf16 v[44:47], v[190:193], v[230:233], v[44:47]
	v_mfma_f32_16x16x32_bf16 v[40:43], v[198:201], v[230:233], v[40:43]
	v_mfma_f32_16x16x32_bf16 v[28:31], v[190:193], v[238:241], v[28:31]
	v_mfma_f32_16x16x32_bf16 v[24:27], v[198:201], v[238:241], v[24:27]
	v_mfma_f32_16x16x32_bf16 v[12:15], v[190:193], v[246:249], v[12:15]
	v_mfma_f32_16x16x32_bf16 v[8:11], v[198:201], v[246:249], v[8:11]
	s_setprio 0
	s_setprio 1
	v_mfma_f32_16x16x32_bf16 v[52:55], v[202:205], v[218:221], v[52:55]
	v_mfma_f32_16x16x32_bf16 v[48:51], v[210:213], v[218:221], v[48:51]
	v_mfma_f32_16x16x32_bf16 v[36:39], v[202:205], v[226:229], v[36:39]
	v_mfma_f32_16x16x32_bf16 v[32:35], v[210:213], v[226:229], v[32:35]
	v_mfma_f32_16x16x32_bf16 v[20:23], v[202:205], v[234:237], v[20:23]
	v_mfma_f32_16x16x32_bf16 v[16:19], v[210:213], v[234:237], v[16:19]
	v_mfma_f32_16x16x32_bf16 v[4:7], v[202:205], v[242:245], v[4:7]
	v_mfma_f32_16x16x32_bf16 v[0:3], v[210:213], v[242:245], v[0:3]
	v_mfma_f32_16x16x32_bf16 v[52:55], v[206:209], v[222:225], v[52:55]
	v_mfma_f32_16x16x32_bf16 v[48:51], v[214:217], v[222:225], v[48:51]
	v_mfma_f32_16x16x32_bf16 v[36:39], v[206:209], v[230:233], v[36:39]
	v_mfma_f32_16x16x32_bf16 v[32:35], v[214:217], v[230:233], v[32:35]
	v_mfma_f32_16x16x32_bf16 v[20:23], v[206:209], v[238:241], v[20:23]
	v_mfma_f32_16x16x32_bf16 v[16:19], v[214:217], v[238:241], v[16:19]
	v_mfma_f32_16x16x32_bf16 v[4:7], v[206:209], v[246:249], v[4:7]
	v_mfma_f32_16x16x32_bf16 v[0:3], v[214:217], v[246:249], v[0:3]
	s_setprio 0
	s_add_i32 s45, s45, 2
	s_add_u32 s36, s36, 0x100
	s_addc_u32 s37, s37, 0
	s_add_u32 s43, s43, 0x100
	s_addc_u32 s44, s44, 0
	s_cmp_gt_u32 s45, 13
	s_barrier
	s_cbranch_scc0 .LBB0_157
	s_and_b64 vcc, exec, s[24:25]
	s_cbranch_vccz .LBB0_160
	s_barrier

; #define PG8_STAGE(bufoff, gbase, voff) do { _Pragma("unroll") for (int _i = 0; _i < 2; ++_i) \
;         __builtin_amdgcn_global_load_lds((const unsigned*)((const char*)(gbase) + (voff)[_i]), (PG8_LAS unsigned*)(lds + (bufoff) + ldsw + _i * 8192), 16, 0, 0); } while (0)
; #define PG8_LDA(dst, b, h) do { _Pragma("unroll") for (int m = 0; m < 4; ++m) _Pragma("unroll") for (int k = 0; k < 2; ++k) dst[m][k] = *(const PG8_LAS bf16x8*)(lds + PG8_SA(b, h) + aoff + m * 2048 + k * 1024); } while (0)
; #define PG8_LDB(dst, b, h) do { _Pragma("unroll") for (int n = 0; n < 2; ++n) _Pragma("unroll") for (int k = 0; k < 2; ++k) dst[n][k] = *(const PG8_LAS bf16x8*)(lds + PG8_SB(b, h) + boff + n * 2048 + k * 1024); } while (0)
; #define PG8_MMA(ai, bj, At, Bt) do { __builtin_amdgcn_s_setprio(1); _Pragma("unroll") for (int m = 0; m < 4; ++m) _Pragma("unroll") for (int n = 0; n < 2; ++n) _Pragma("unroll") for (int k = 0; k < 2; ++k) \
;         acc[ai][bj][m][n] = __builtin_amdgcn_mfma_f32_16x16x32_bf16(Bt[n][k], At[m][k], acc[ai][bj][m][n], 0, 0, 0); __builtin_amdgcn_s_setprio(0); } while (0)
; #define PG8_WAIT_V(n) asm volatile("s_waitcnt vmcnt(" #n ")" ::: "memory")
; #define PG8_WAIT_L(n) asm volatile("s_waitcnt lgkmcnt(" #n ")" ::: "memory")
; #define PG8_BAR __builtin_amdgcn_s_barrier()
; template <class Epi, class Sched, bool ALIGN_EPI = false, bool SP2 = false>
; __device__ __forceinline__ void gemm_phase(PG8_LAS unsigned char* lds, const Gemm g, const Sched& S, const Epi& E) {
;     ...
;             const char* a1 = cA + (size_t)(t + 1) * kstep;
;             const char* a2 = last ? nA : cA + (size_t)(t + 2) * kstep; const char* b2 = last ? nB : cB + (size_t)(t + 2) * kstep;
;             const char* a3 = a2 + kstep; const char* b3 = b2 + kstep;
;             if (last && has_next) S.a_ready(nxt);
;             if constexpr (SP2) {
;             PG8_LDB(B0, 0, 0); PG8_LDB(B1, 0, 1); PG8_SCHED; PG8_LDA(At, 0, 0); PG8_STAGE(PG8_SA(1, 1), a1 + hstepA, voffA);
;             PG8_WAIT_V(8); PG8_WAIT_L(0); PG8_BAR; PG8_MMA(0, 0, At, B0); PG8_MMA(0, 1, At, B1); PG8_BAR; PG8_SCHED;
;             PG8_LDA(At, 0, 1); PG8_STAGE(PG8_SB(0, 0), b2, voffB); PG8_STAGE(PG8_SB(0, 1), b2 + hstepB, voffB); PG8_STAGE(PG8_SA(0, 0), a2, voffA);
;             PG8_WAIT_V(8); PG8_WAIT_L(0); PG8_BAR; PG8_MMA(1, 0, At, B0); PG8_MMA(1, 1, At, B1); PG8_BAR; PG8_SCHED;
.LBB0_470:
	ds_read_b128 v[158:161], v155
	ds_read_b128 v[162:165], v155 offset:1024
	ds_read_b128 v[166:169], v155 offset:2048
	ds_read_b128 v[170:173], v155 offset:3072
	ds_read_b128 v[174:177], v156
	ds_read_b128 v[178:181], v156 offset:1024
	ds_read_b128 v[186:189], v156 offset:2048
	ds_read_b128 v[190:193], v156 offset:3072
	s_add_u32 s12, s0, 0xfffc0080
	s_addc_u32 s13, s1, -1
	s_cmp_eq_u32 s44, 4
	s_cselect_b32 s17, s38, s13
	s_cselect_b32 s16, s39, s12
	s_cselect_b32 s13, s40, s43
	s_cselect_b32 s12, s41, s42
	v_lshl_add_u64 v[182:183], s[0:1], 0, v[140:141]
	s_add_i32 m0, s22, 0xc000
	ds_read_b128 v[194:197], v157
	ds_read_b128 v[198:201], v157 offset:1024
	ds_read_b128 v[202:205], v157 offset:2048
	ds_read_b128 v[206:209], v157 offset:3072
	ds_read_b128 v[210:213], v157 offset:4096
	ds_read_b128 v[214:217], v157 offset:5120
	ds_read_b128 v[218:221], v157 offset:6144
	ds_read_b128 v[222:225], v157 offset:7168
	global_load_lds_dwordx4 v[182:183], off
	v_lshl_add_u64 v[182:183], s[0:1], 0, v[142:143]
	s_add_i32 m0, s22, 0xe000
	s_nop 0
	global_load_lds_dwordx4 v[182:183], off
	s_waitcnt vmcnt(8)
	s_waitcnt lgkmcnt(0)
	s_barrier
	s_setprio 1
	s_waitcnt lgkmcnt(0)
	v_mfma_f32_16x16x32_bf16 v[124:127], v[158:161], v[194:197], v[124:127]
	v_mfma_f32_16x16x32_bf16 v[120:123], v[166:169], v[194:197], v[120:123]
	v_mfma_f32_16x16x32_bf16 v[116:119], v[158:161], v[202:205], v[116:119]
	v_mfma_f32_16x16x32_bf16 v[112:115], v[166:169], v[202:205], v[112:115]
	v_mfma_f32_16x16x32_bf16 v[108:111], v[158:161], v[210:213], v[108:111]
	v_mfma_f32_16x16x32_bf16 v[100:103], v[166:169], v[210:213], v[100:103]
	v_mfma_f32_16x16x32_bf16 v[92:95], v[158:161], v[218:221], v[92:95]
	v_mfma_f32_16x16x32_bf16 v[84:87], v[166:169], v[218:221], v[84:87]
	v_mfma_f32_16x16x32_bf16 v[124:127], v[162:165], v[198:201], v[124:127]
	v_mfma_f32_16x16x32_bf16 v[120:123], v[170:173], v[198:201], v[120:123]
	v_mfma_f32_16x16x32_bf16 v[116:119], v[162:165], v[206:209], v[116:119]
	v_mfma_f32_16x16x32_bf16 v[112:115], v[170:173], v[206:209], v[112:115]
	v_mfma_f32_16x16x32_bf16 v[108:111], v[162:165], v[214:217], v[108:111]
	v_mfma_f32_16x16x32_bf16 v[100:103], v[170:173], v[214:217], v[100:103]
	v_mfma_f32_16x16x32_bf16 v[92:95], v[162:165], v[222:225], v[92:95]
	v_mfma_f32_16x16x32_bf16 v[84:87], v[170:173], v[222:225], v[84:87]
	s_setprio 0
	s_setprio 1
	v_mfma_f32_16x16x32_bf16 v[104:107], v[174:177], v[194:197], v[104:107]
	v_mfma_f32_16x16x32_bf16 v[96:99], v[186:189], v[194:197], v[96:99]
	v_mfma_f32_16x16x32_bf16 v[88:91], v[174:177], v[202:205], v[88:91]
	v_mfma_f32_16x16x32_bf16 v[80:83], v[186:189], v[202:205], v[80:83]
	v_mfma_f32_16x16x32_bf16 v[76:79], v[174:177], v[210:213], v[76:79]
	v_mfma_f32_16x16x32_bf16 v[72:75], v[186:189], v[210:213], v[72:75]
	v_mfma_f32_16x16x32_bf16 v[68:71], v[174:177], v[218:221], v[68:71]
	v_mfma_f32_16x16x32_bf16 v[64:67], v[186:189], v[218:221], v[64:67]
	v_mfma_f32_16x16x32_bf16 v[104:107], v[178:181], v[198:201], v[104:107]
	v_mfma_f32_16x16x32_bf16 v[96:99], v[190:193], v[198:201], v[96:99]
	v_mfma_f32_16x16x32_bf16 v[88:91], v[178:181], v[206:209], v[88:91]
	v_mfma_f32_16x16x32_bf16 v[80:83], v[190:193], v[206:209], v[80:83]
	v_mfma_f32_16x16x32_bf16 v[76:79], v[178:181], v[214:217], v[76:79]
	v_mfma_f32_16x16x32_bf16 v[72:75], v[190:193], v[214:217], v[72:75]
	v_mfma_f32_16x16x32_bf16 v[68:71], v[178:181], v[222:225], v[68:71]
	v_mfma_f32_16x16x32_bf16 v[64:67], v[190:193], v[222:225], v[64:67]
	s_setprio 0
	s_barrier
	s_add_i32 s45, s33, s15
	v_lshl_add_u64 v[182:183], s[12:13], 0, v[132:133]
	s_mov_b32 m0, s45
	ds_read_b128 v[194:197], v157 offset:16384
	ds_read_b128 v[198:201], v157 offset:17408
	ds_read_b128 v[202:205], v157 offset:18432
	ds_read_b128 v[206:209], v157 offset:19456
	ds_read_b128 v[210:213], v157 offset:20480
	ds_read_b128 v[214:217], v157 offset:21504
	ds_read_b128 v[218:221], v157 offset:22528
	ds_read_b128 v[222:225], v157 offset:23552
	global_load_lds_dwordx4 v[182:183], off
	s_add_i32 m0, s45, 0x2000
	s_add_u32 s46, s12, 0x80000
	v_lshl_add_u64 v[226:227], s[12:13], 0, v[128:129]
	s_addc_u32 s47, s13, 0
	s_add_i32 s45, s34, s15
	global_load_lds_dwordx4 v[226:227], off
	v_lshl_add_u64 v[228:229], s[46:47], 0, v[132:133]
	s_mov_b32 m0, s45
	v_lshl_add_u64 v[230:231], s[16:17], 0, v[130:131]
	global_load_lds_dwordx4 v[228:229], off
	v_lshl_add_u64 v[228:229], s[46:47], 0, v[128:129]
	s_add_i32 m0, s45, 0x2000
	s_nop 0
	global_load_lds_dwordx4 v[228:229], off
	v_lshl_add_u64 v[228:229], s[16:17], 0, v[134:135]
	s_mov_b32 m0, s22
	s_nop 0
	global_load_lds_dwordx4 v[228:229], off
	s_mov_b32 m0, s25
	s_nop 0
	global_load_lds_dwordx4 v[230:231], off
	s_waitcnt vmcnt(8)
	s_waitcnt lgkmcnt(0)
	s_barrier
; #define PG8_STAGE(bufoff, gbase, voff) do { _Pragma("unroll") for (int _i = 0; _i < 2; ++_i) \
;         __builtin_amdgcn_global_load_lds((const unsigned*)((const char*)(gbase) + (voff)[_i]), (PG8_LAS unsigned*)(lds + (bufoff) + ldsw + _i * 8192), 16, 0, 0); } while (0)
; #define PG8_LDA(dst, b, h) do { _Pragma("unroll") for (int m = 0; m < 4; ++m) _Pragma("unroll") for (int k = 0; k < 2; ++k) dst[m][k] = *(const PG8_LAS bf16x8*)(lds + PG8_SA(b, h) + aoff + m * 2048 + k * 1024); } while (0)
; #define PG8_LDB(dst, b, h) do { _Pragma("unroll") for (int n = 0; n < 2; ++n) _Pragma("unroll") for (int k = 0; k < 2; ++k) dst[n][k] = *(const PG8_LAS bf16x8*)(lds + PG8_SB(b, h) + boff + n * 2048 + k * 1024); } while (0)
; #define PG8_MMA(ai, bj, At, Bt) do { __builtin_amdgcn_s_setprio(1); _Pragma("unroll") for (int m = 0; m < 4; ++m) _Pragma("unroll") for (int n = 0; n < 2; ++n) _Pragma("unroll") for (int k = 0; k < 2; ++k) \
;         acc[ai][bj][m][n] = __builtin_amdgcn_mfma_f32_16x16x32_bf16(Bt[n][k], At[m][k], acc[ai][bj][m][n], 0, 0, 0); __builtin_amdgcn_s_setprio(0); } while (0)
; #define PG8_WAIT_V(n) asm volatile("s_waitcnt vmcnt(" #n ")" ::: "memory")
; #define PG8_WAIT_L(n) asm volatile("s_waitcnt lgkmcnt(" #n ")" ::: "memory")
; #define PG8_BAR __builtin_amdgcn_s_barrier()
; #define PG8_SCHED __builtin_amdgcn_sched_barrier(0)
; template <class Epi, class Sched, bool ALIGN_EPI = false, bool SP2 = false>
; __device__ __forceinline__ void gemm_phase(PG8_LAS unsigned char* lds, const Gemm g, const Sched& S, const Epi& E) {
;     ...
;             PG8_WAIT_V(8); PG8_WAIT_L(0); PG8_BAR; PG8_MMA(1, 0, At, B0); PG8_MMA(1, 1, At, B1); PG8_BAR; PG8_SCHED;
;             PG8_LDB(B0, 1, 0); PG8_LDB(B1, 1, 1); PG8_SCHED; PG8_LDA(At, 1, 0); PG8_STAGE(PG8_SA(0, 1), a2 + hstepA, voffA);
;             PG8_WAIT_V(8); PG8_WAIT_L(0); PG8_BAR; PG8_MMA(0, 0, At, B0); PG8_MMA(0, 1, At, B1); PG8_BAR; PG8_SCHED;
	s_setprio 1
	s_waitcnt lgkmcnt(0)
	v_mfma_f32_16x16x32_bf16 v[60:63], v[158:161], v[194:197], v[60:63]
	v_mfma_f32_16x16x32_bf16 v[56:59], v[166:169], v[194:197], v[56:59]
	v_mfma_f32_16x16x32_bf16 v[52:55], v[158:161], v[202:205], v[52:55]
	v_mfma_f32_16x16x32_bf16 v[48:51], v[166:169], v[202:205], v[48:51]
	v_mfma_f32_16x16x32_bf16 v[44:47], v[158:161], v[210:213], v[44:47]
	v_mfma_f32_16x16x32_bf16 v[36:39], v[166:169], v[210:213], v[36:39]
	v_mfma_f32_16x16x32_bf16 v[28:31], v[158:161], v[218:221], v[28:31]
	v_mfma_f32_16x16x32_bf16 v[20:23], v[166:169], v[218:221], v[20:23]
	v_mfma_f32_16x16x32_bf16 v[60:63], v[162:165], v[198:201], v[60:63]
	v_mfma_f32_16x16x32_bf16 v[56:59], v[170:173], v[198:201], v[56:59]
	v_mfma_f32_16x16x32_bf16 v[52:55], v[162:165], v[206:209], v[52:55]
	v_mfma_f32_16x16x32_bf16 v[48:51], v[170:173], v[206:209], v[48:51]
	v_mfma_f32_16x16x32_bf16 v[44:47], v[162:165], v[214:217], v[44:47]
	v_mfma_f32_16x16x32_bf16 v[36:39], v[170:173], v[214:217], v[36:39]
	v_mfma_f32_16x16x32_bf16 v[28:31], v[162:165], v[222:225], v[28:31]
	v_mfma_f32_16x16x32_bf16 v[20:23], v[170:173], v[222:225], v[20:23]
	s_setprio 0
	s_setprio 1
	v_mfma_f32_16x16x32_bf16 v[40:43], v[174:177], v[194:197], v[40:43]
	v_mfma_f32_16x16x32_bf16 v[32:35], v[186:189], v[194:197], v[32:35]
	v_mfma_f32_16x16x32_bf16 v[24:27], v[174:177], v[202:205], v[24:27]
	v_mfma_f32_16x16x32_bf16 v[16:19], v[186:189], v[202:205], v[16:19]
	v_mfma_f32_16x16x32_bf16 v[12:15], v[174:177], v[210:213], v[12:15]
	v_mfma_f32_16x16x32_bf16 v[8:11], v[186:189], v[210:213], v[8:11]
	v_mfma_f32_16x16x32_bf16 v[4:7], v[174:177], v[218:221], v[4:7]
	v_mfma_f32_16x16x32_bf16 v[0:3], v[186:189], v[218:221], v[0:3]
	v_mfma_f32_16x16x32_bf16 v[40:43], v[178:181], v[198:201], v[40:43]
	v_mfma_f32_16x16x32_bf16 v[32:35], v[190:193], v[198:201], v[32:35]
	v_mfma_f32_16x16x32_bf16 v[24:27], v[178:181], v[206:209], v[24:27]
	v_mfma_f32_16x16x32_bf16 v[16:19], v[190:193], v[206:209], v[16:19]
	v_mfma_f32_16x16x32_bf16 v[12:15], v[178:181], v[214:217], v[12:15]
	v_mfma_f32_16x16x32_bf16 v[8:11], v[190:193], v[214:217], v[8:11]
	v_mfma_f32_16x16x32_bf16 v[4:7], v[178:181], v[222:225], v[4:7]
	v_mfma_f32_16x16x32_bf16 v[0:3], v[190:193], v[222:225], v[0:3]
	s_setprio 0
	s_barrier
	s_add_i32 s45, 0, 0x18000
	v_add_u32_e32 v136, s45, v150
	s_add_i32 s46, 0, 0x1c000
	ds_read_b128 v[158:161], v136
	ds_read_b128 v[162:165], v136 offset:1024
	ds_read_b128 v[166:169], v136 offset:2048
	ds_read_b128 v[170:173], v136 offset:3072
	v_add_u32_e32 v136, s46, v150
	ds_read_b128 v[174:177], v136
	ds_read_b128 v[178:181], v136 offset:1024
	ds_read_b128 v[186:189], v136 offset:2048
	ds_read_b128 v[190:193], v136 offset:3072
	s_add_u32 s16, s16, 0x40000
	s_addc_u32 s17, s17, 0
	s_mov_b32 m0, s26
	v_lshl_add_u64 v[232:233], s[16:17], 0, v[134:135]
	ds_read_b128 v[194:197], v157 offset:32768
	ds_read_b128 v[198:201], v157 offset:33792
	ds_read_b128 v[202:205], v157 offset:34816
	ds_read_b128 v[206:209], v157 offset:35840
	ds_read_b128 v[210:213], v157 offset:36864
	ds_read_b128 v[214:217], v157 offset:37888
	ds_read_b128 v[218:221], v157 offset:38912
	ds_read_b128 v[222:225], v157 offset:39936
	global_load_lds_dwordx4 v[232:233], off
	v_lshl_add_u64 v[232:233], s[16:17], 0, v[130:131]
	s_mov_b32 m0, s27
	s_nop 0
	global_load_lds_dwordx4 v[232:233], off
	s_waitcnt vmcnt(8)
	s_waitcnt lgkmcnt(0)
	s_barrier
	s_setprio 1
	s_waitcnt lgkmcnt(0)
	v_mfma_f32_16x16x32_bf16 v[124:127], v[158:161], v[194:197], v[124:127]
	v_mfma_f32_16x16x32_bf16 v[120:123], v[166:169], v[194:197], v[120:123]
	v_mfma_f32_16x16x32_bf16 v[116:119], v[158:161], v[202:205], v[116:119]
	v_mfma_f32_16x16x32_bf16 v[112:115], v[166:169], v[202:205], v[112:115]
	v_mfma_f32_16x16x32_bf16 v[108:111], v[158:161], v[210:213], v[108:111]
	v_mfma_f32_16x16x32_bf16 v[100:103], v[166:169], v[210:213], v[100:103]
	v_mfma_f32_16x16x32_bf16 v[92:95], v[158:161], v[218:221], v[92:95]
	v_mfma_f32_16x16x32_bf16 v[84:87], v[166:169], v[218:221], v[84:87]
	v_mfma_f32_16x16x32_bf16 v[124:127], v[162:165], v[198:201], v[124:127]
	v_mfma_f32_16x16x32_bf16 v[120:123], v[170:173], v[198:201], v[120:123]
	v_mfma_f32_16x16x32_bf16 v[116:119], v[162:165], v[206:209], v[116:119]
	v_mfma_f32_16x16x32_bf16 v[112:115], v[170:173], v[206:209], v[112:115]
	v_mfma_f32_16x16x32_bf16 v[108:111], v[162:165], v[214:217], v[108:111]
	v_mfma_f32_16x16x32_bf16 v[100:103], v[170:173], v[214:217], v[100:103]
	v_mfma_f32_16x16x32_bf16 v[92:95], v[162:165], v[222:225], v[92:95]
	v_mfma_f32_16x16x32_bf16 v[84:87], v[170:173], v[222:225], v[84:87]
	s_setprio 0
	s_setprio 1
	v_mfma_f32_16x16x32_bf16 v[104:107], v[174:177], v[194:197], v[104:107]
	v_mfma_f32_16x16x32_bf16 v[96:99], v[186:189], v[194:197], v[96:99]
	v_mfma_f32_16x16x32_bf16 v[88:91], v[174:177], v[202:205], v[88:91]
	v_mfma_f32_16x16x32_bf16 v[80:83], v[186:189], v[202:205], v[80:83]
	v_mfma_f32_16x16x32_bf16 v[76:79], v[174:177], v[210:213], v[76:79]
	v_mfma_f32_16x16x32_bf16 v[72:75], v[186:189], v[210:213], v[72:75]
	v_mfma_f32_16x16x32_bf16 v[68:71], v[174:177], v[218:221], v[68:71]
	v_mfma_f32_16x16x32_bf16 v[64:67], v[186:189], v[218:221], v[64:67]
	v_mfma_f32_16x16x32_bf16 v[104:107], v[178:181], v[198:201], v[104:107]
	v_mfma_f32_16x16x32_bf16 v[96:99], v[190:193], v[198:201], v[96:99]
	v_mfma_f32_16x16x32_bf16 v[88:91], v[178:181], v[206:209], v[88:91]
	v_mfma_f32_16x16x32_bf16 v[80:83], v[190:193], v[206:209], v[80:83]
	v_mfma_f32_16x16x32_bf16 v[76:79], v[178:181], v[214:217], v[76:79]
	v_mfma_f32_16x16x32_bf16 v[72:75], v[190:193], v[214:217], v[72:75]
	v_mfma_f32_16x16x32_bf16 v[68:71], v[178:181], v[222:225], v[68:71]
	v_mfma_f32_16x16x32_bf16 v[64:67], v[190:193], v[222:225], v[64:67]
	s_setprio 0
	s_barrier
; #define PG8_STAGE(bufoff, gbase, voff) do { _Pragma("unroll") for (int _i = 0; _i < 2; ++_i) \
;         __builtin_amdgcn_global_load_lds((const unsigned*)((const char*)(gbase) + (voff)[_i]), (PG8_LAS unsigned*)(lds + (bufoff) + ldsw + _i * 8192), 16, 0, 0); } while (0)
; #define PG8_LDA(dst, b, h) do { _Pragma("unroll") for (int m = 0; m < 4; ++m) _Pragma("unroll") for (int k = 0; k < 2; ++k) dst[m][k] = *(const PG8_LAS bf16x8*)(lds + PG8_SA(b, h) + aoff + m * 2048 + k * 1024); } while (0)
; #define PG8_MMA(ai, bj, At, Bt) do { __builtin_amdgcn_s_setprio(1); _Pragma("unroll") for (int m = 0; m < 4; ++m) _Pragma("unroll") for (int n = 0; n < 2; ++n) _Pragma("unroll") for (int k = 0; k < 2; ++k) \
;         acc[ai][bj][m][n] = __builtin_amdgcn_mfma_f32_16x16x32_bf16(Bt[n][k], At[m][k], acc[ai][bj][m][n], 0, 0, 0); __builtin_amdgcn_s_setprio(0); } while (0)
; #define PG8_WAIT_V(n) asm volatile("s_waitcnt vmcnt(" #n ")" ::: "memory")
; #define PG8_WAIT_L(n) asm volatile("s_waitcnt lgkmcnt(" #n ")" ::: "memory")
; #define PG8_BAR __builtin_amdgcn_s_barrier()
; #define PG8_SCHED __builtin_amdgcn_sched_barrier(0)
; template <class Epi, class Sched, bool ALIGN_EPI = false, bool SP2 = false>
; __device__ __forceinline__ void gemm_phase(PG8_LAS unsigned char* lds, const Gemm g, const Sched& S, const Epi& E) {
;     ...
;         for (int t = 0; t < nt; t += 2) {
;     ...
;             PG8_LDA(At, 1, 1); PG8_STAGE(PG8_SB(1, 0), b3, voffB); PG8_STAGE(PG8_SB(1, 1), b3 + hstepB, voffB); PG8_STAGE(PG8_SA(1, 0), a3, voffA);
;             PG8_WAIT_V(8); PG8_WAIT_L(0); PG8_BAR; PG8_MMA(1, 0, At, B0); PG8_MMA(1, 1, At, B1); PG8_BAR; PG8_SCHED;
;     __device__ __forceinline__ void operator()(const f32x4 (&acc)[2][2][4][2], const pg8::Unit& u, int wr, int wc, int fr, int fq) const {
;         float* base = part + (size_t)(u.koff >> 10) * 8192 * 256;
; #pragma unroll
;         for (int ai = 0; ai < 2; ++ai)
; #pragma unroll
;             for (int m = 0; m < 4; ++m) {
;                 const int row = u.pm * 256 + ai * 128 + wr * 64 + m * 16 + fr;
; #pragma unroll
;                 for (int bj = 0; bj < 2; ++bj) {
;                     float* p = base + (size_t)row * 256 + 128 * bj + 32 * wc + 8 * fq;
;                     *(f32x4*)p = acc[ai][bj][m][0]; *(f32x4*)(p + 4) = acc[ai][bj][m][1];
;                 }
;             }
	s_add_i32 s16, s45, s15
	v_lshl_add_u64 v[182:183], v[182:183], 0, s[10:11]
	s_mov_b32 m0, s16
	ds_read_b128 v[194:197], v157 offset:49152
	ds_read_b128 v[198:201], v157 offset:50176
	ds_read_b128 v[202:205], v157 offset:51200
	ds_read_b128 v[206:209], v157 offset:52224
	ds_read_b128 v[210:213], v157 offset:53248
	ds_read_b128 v[214:217], v157 offset:54272
	ds_read_b128 v[218:221], v157 offset:55296
	ds_read_b128 v[222:225], v157 offset:56320
	global_load_lds_dwordx4 v[182:183], off
	s_add_i32 m0, s16, 0x2000
	s_add_u32 s12, s12, 0x80080
	v_lshl_add_u64 v[182:183], v[226:227], 0, s[10:11]
	s_addc_u32 s13, s13, 0
	s_add_i32 s16, s46, s15
	global_load_lds_dwordx4 v[182:183], off
	v_lshl_add_u64 v[182:183], s[12:13], 0, v[132:133]
	s_mov_b32 m0, s16
	s_nop 0
	global_load_lds_dwordx4 v[182:183], off
	v_lshl_add_u64 v[182:183], s[12:13], 0, v[128:129]
	s_add_i32 m0, s16, 0x2000
	s_nop 0
	global_load_lds_dwordx4 v[182:183], off
	v_lshl_add_u64 v[182:183], v[228:229], 0, s[10:11]
	s_mov_b32 m0, s30
	s_nop 0
	global_load_lds_dwordx4 v[182:183], off
	v_lshl_add_u64 v[182:183], v[230:231], 0, s[10:11]
	s_mov_b32 m0, s31
	s_nop 0
	global_load_lds_dwordx4 v[182:183], off
	s_waitcnt vmcnt(8)
	s_waitcnt lgkmcnt(0)
	s_barrier
	s_setprio 1
	s_waitcnt lgkmcnt(0)
	v_mfma_f32_16x16x32_bf16 v[60:63], v[158:161], v[194:197], v[60:63]
	v_mfma_f32_16x16x32_bf16 v[56:59], v[166:169], v[194:197], v[56:59]
	v_mfma_f32_16x16x32_bf16 v[52:55], v[158:161], v[202:205], v[52:55]
	v_mfma_f32_16x16x32_bf16 v[48:51], v[166:169], v[202:205], v[48:51]
	v_mfma_f32_16x16x32_bf16 v[44:47], v[158:161], v[210:213], v[44:47]
	v_mfma_f32_16x16x32_bf16 v[36:39], v[166:169], v[210:213], v[36:39]
	v_mfma_f32_16x16x32_bf16 v[28:31], v[158:161], v[218:221], v[28:31]
	v_mfma_f32_16x16x32_bf16 v[20:23], v[166:169], v[218:221], v[20:23]
	v_mfma_f32_16x16x32_bf16 v[60:63], v[162:165], v[198:201], v[60:63]
	v_mfma_f32_16x16x32_bf16 v[56:59], v[170:173], v[198:201], v[56:59]
	v_mfma_f32_16x16x32_bf16 v[52:55], v[162:165], v[206:209], v[52:55]
	v_mfma_f32_16x16x32_bf16 v[48:51], v[170:173], v[206:209], v[48:51]
	v_mfma_f32_16x16x32_bf16 v[44:47], v[162:165], v[214:217], v[44:47]
	v_mfma_f32_16x16x32_bf16 v[36:39], v[170:173], v[214:217], v[36:39]
	v_mfma_f32_16x16x32_bf16 v[28:31], v[162:165], v[222:225], v[28:31]
	v_mfma_f32_16x16x32_bf16 v[20:23], v[170:173], v[222:225], v[20:23]
	s_setprio 0
	s_setprio 1
	v_mfma_f32_16x16x32_bf16 v[40:43], v[174:177], v[194:197], v[40:43]
	v_mfma_f32_16x16x32_bf16 v[32:35], v[186:189], v[194:197], v[32:35]
	v_mfma_f32_16x16x32_bf16 v[24:27], v[174:177], v[202:205], v[24:27]
	v_mfma_f32_16x16x32_bf16 v[16:19], v[186:189], v[202:205], v[16:19]
	v_mfma_f32_16x16x32_bf16 v[12:15], v[174:177], v[210:213], v[12:15]
	v_mfma_f32_16x16x32_bf16 v[8:11], v[186:189], v[210:213], v[8:11]
	v_mfma_f32_16x16x32_bf16 v[4:7], v[174:177], v[218:221], v[4:7]
	v_mfma_f32_16x16x32_bf16 v[0:3], v[186:189], v[218:221], v[0:3]
	v_mfma_f32_16x16x32_bf16 v[40:43], v[178:181], v[198:201], v[40:43]
	v_mfma_f32_16x16x32_bf16 v[32:35], v[190:193], v[198:201], v[32:35]
	v_mfma_f32_16x16x32_bf16 v[24:27], v[178:181], v[206:209], v[24:27]
	v_mfma_f32_16x16x32_bf16 v[16:19], v[190:193], v[206:209], v[16:19]
	v_mfma_f32_16x16x32_bf16 v[12:15], v[178:181], v[214:217], v[12:15]
	v_mfma_f32_16x16x32_bf16 v[8:11], v[190:193], v[214:217], v[8:11]
	v_mfma_f32_16x16x32_bf16 v[4:7], v[178:181], v[222:225], v[4:7]
	v_mfma_f32_16x16x32_bf16 v[0:3], v[190:193], v[222:225], v[0:3]
	s_setprio 0
	s_add_i32 s44, s44, 2
	s_add_u32 s0, s0, 0x100
	s_addc_u32 s1, s1, 0
	s_add_u32 s42, s42, 0x100
	s_addc_u32 s43, s43, 0
	s_cmp_gt_u32 s44, 5
	s_barrier
	s_cbranch_scc0 .LBB0_470
	s_ashr_i32 s0, s24, 10
	s_ashr_i32 s1, s0, 31
	s_lshl_b64 s[0:1], s[0:1], 23
	v_lshl_add_u64 v[158:159], v[138:139], 0, s[0:1]
	s_lshl_b32 s0, s23, 8
	v_add_u32_e32 v136, s0, v148
	v_lshlrev_b64 v[160:161], 10, v[136:137]
	v_lshl_add_u64 v[160:161], v[158:159], 0, v[160:161]
	global_store_dwordx4 v[160:161], v[124:127], off
	global_store_dwordx4 v[160:161], v[120:123], off offset:16
	global_store_dwordx4 v[160:161], v[104:107], off offset:512
	global_store_dwordx4 v[160:161], v[96:99], off offset:528
	s_and_b64 vcc, exec, vcc
	s_mov_b32 s24, s35
	v_add_u32_e32 v96, s0, v152
	v_mov_b32_e32 v97, v137
	v_lshlrev_b64 v[96:97], 10, v[96:97]
	v_lshl_add_u64 v[96:97], v[158:159], 0, v[96:97]
	global_store_dwordx4 v[96:97], v[116:119], off
	global_store_dwordx4 v[96:97], v[112:115], off offset:16
	global_store_dwordx4 v[96:97], v[88:91], off offset:512
	global_store_dwordx4 v[96:97], v[80:83], off offset:528
	s_mov_b32 s23, s37
	s_nop 0
	v_add_u32_e32 v80, s0, v153
	v_mov_b32_e32 v81, v137
	v_lshlrev_b64 v[80:81], 10, v[80:81]
	v_lshl_add_u64 v[80:81], v[158:159], 0, v[80:81]
	global_store_dwordx4 v[80:81], v[108:111], off
	global_store_dwordx4 v[80:81], v[100:103], off offset:16
	global_store_dwordx4 v[80:81], v[76:79], off offset:512
	global_store_dwordx4 v[80:81], v[72:75], off offset:528
	s_nop 1
	v_add_u32_e32 v72, s0, v154
	v_mov_b32_e32 v73, v137
	v_lshlrev_b64 v[72:73], 10, v[72:73]
	v_lshl_add_u64 v[72:73], v[158:159], 0, v[72:73]
	global_store_dwordx4 v[72:73], v[92:95], off
	global_store_dwordx4 v[72:73], v[84:87], off offset:16
	global_store_dwordx4 v[72:73], v[68:71], off offset:512
	global_store_dwordx4 v[72:73], v[64:67], off offset:528
	s_nop 1
	v_add_u32_e32 v64, 0x80, v136
	v_mov_b32_e32 v65, v137
	v_lshlrev_b64 v[64:65], 10, v[64:65]
	v_lshl_add_u64 v[64:65], v[158:159], 0, v[64:65]
	global_store_dwordx4 v[64:65], v[60:63], off
	global_store_dwordx4 v[64:65], v[56:59], off offset:16
	global_store_dwordx4 v[64:65], v[40:43], off offset:512
	global_store_dwordx4 v[64:65], v[32:35], off offset:528
	s_nop 1
	v_add_u32_e32 v32, 0x90, v136
	v_mov_b32_e32 v33, v137
	v_lshlrev_b64 v[32:33], 10, v[32:33]
	v_lshl_add_u64 v[32:33], v[158:159], 0, v[32:33]
	global_store_dwordx4 v[32:33], v[52:55], off
	global_store_dwordx4 v[32:33], v[48:51], off offset:16
	global_store_dwordx4 v[32:33], v[24:27], off offset:512
	global_store_dwordx4 v[32:33], v[16:19], off offset:528
	s_nop 1
	v_add_u32_e32 v16, 0xa0, v136
	v_mov_b32_e32 v17, v137
	v_lshlrev_b64 v[16:17], 10, v[16:17]
	v_lshl_add_u64 v[16:17], v[158:159], 0, v[16:17]
	v_add_u32_e32 v136, 0xb0, v136
	global_store_dwordx4 v[16:17], v[44:47], off
	global_store_dwordx4 v[16:17], v[36:39], off offset:16
	global_store_dwordx4 v[16:17], v[12:15], off offset:512
	global_store_dwordx4 v[16:17], v[8:11], off offset:528
	s_nop 1
	v_lshlrev_b64 v[8:9], 10, v[136:137]
	v_lshl_add_u64 v[8:9], v[158:159], 0, v[8:9]
	global_store_dwordx4 v[8:9], v[28:31], off
	global_store_dwordx4 v[8:9], v[20:23], off offset:16
	global_store_dwordx4 v[8:9], v[4:7], off offset:512
	global_store_dwordx4 v[8:9], v[0:3], off offset:528
	s_cbranch_vccz .LBB0_469
	s_waitcnt vmcnt(0)
	s_cmpk_gt_u32 s14, 0xff
	s_cbranch_scc1 .LBB0_474
	s_barrier

; #define PG8_STAGE(bufoff, gbase, voff) do { _Pragma("unroll") for (int _i = 0; _i < 2; ++_i) \
;         __builtin_amdgcn_global_load_lds((const unsigned*)((const char*)(gbase) + (voff)[_i]), (PG8_LAS unsigned*)(lds + (bufoff) + ldsw + _i * 8192), 16, 0, 0); } while (0)
; #define PG8_LDA(dst, b, h) do { _Pragma("unroll") for (int m = 0; m < 4; ++m) _Pragma("unroll") for (int k = 0; k < 2; ++k) dst[m][k] = *(const PG8_LAS bf16x8*)(lds + PG8_SA(b, h) + aoff + m * 2048 + k * 1024); } while (0)
; #define PG8_LDB(dst, b, h) do { _Pragma("unroll") for (int n = 0; n < 2; ++n) _Pragma("unroll") for (int k = 0; k < 2; ++k) dst[n][k] = *(const PG8_LAS bf16x8*)(lds + PG8_SB(b, h) + boff + n * 2048 + k * 1024); } while (0)
; #define PG8_MMA(ai, bj, At, Bt) do { __builtin_amdgcn_s_setprio(1); _Pragma("unroll") for (int m = 0; m < 4; ++m) _Pragma("unroll") for (int n = 0; n < 2; ++n) _Pragma("unroll") for (int k = 0; k < 2; ++k) \
;         acc[ai][bj][m][n] = __builtin_amdgcn_mfma_f32_16x16x32_bf16(Bt[n][k], At[m][k], acc[ai][bj][m][n], 0, 0, 0); __builtin_amdgcn_s_setprio(0); } while (0)
; #define PG8_WAIT_V(n) asm volatile("s_waitcnt vmcnt(" #n ")" ::: "memory")
; #define PG8_WAIT_L(n) asm volatile("s_waitcnt lgkmcnt(" #n ")" ::: "memory")
; #define PG8_BAR __builtin_amdgcn_s_barrier()
; template <class Epi, class Sched, bool ALIGN_EPI = false, bool SP2 = false>
; __device__ __forceinline__ void gemm_phase(PG8_LAS unsigned char* lds, const Gemm g, const Sched& S, const Epi& E) {
;     ...
;             const char* a1 = cA + (size_t)(t + 1) * kstep;
;             const char* a2 = last ? nA : cA + (size_t)(t + 2) * kstep; const char* b2 = last ? nB : cB + (size_t)(t + 2) * kstep;
;             const char* a3 = a2 + kstep; const char* b3 = b2 + kstep;
;             if (last && has_next) S.a_ready(nxt);
;             if constexpr (SP2) {
;             PG8_LDB(B0, 0, 0); PG8_LDB(B1, 0, 1); PG8_SCHED; PG8_LDA(At, 0, 0); PG8_STAGE(PG8_SA(1, 1), a1 + hstepA, voffA);
;             PG8_WAIT_V(8); PG8_WAIT_L(0); PG8_BAR; PG8_MMA(0, 0, At, B0); PG8_MMA(0, 1, At, B1); PG8_BAR; PG8_SCHED;
;             PG8_LDA(At, 0, 1); PG8_STAGE(PG8_SB(0, 0), b2, voffB); PG8_STAGE(PG8_SB(0, 1), b2 + hstepB, voffB); PG8_STAGE(PG8_SA(0, 0), a2, voffA);
;             PG8_WAIT_V(8); PG8_WAIT_L(0); PG8_BAR; PG8_MMA(1, 0, At, B0); PG8_MMA(1, 1, At, B1); PG8_BAR; PG8_SCHED;
.LBB0_935:
	ds_read_b128 v[120:123], v237
	ds_read_b128 v[124:127], v237 offset:1024
	ds_read_b128 v[136:139], v237 offset:2048
	ds_read_b128 v[140:143], v237 offset:3072
	ds_read_b128 v[144:147], v238
	ds_read_b128 v[148:151], v238 offset:1024
	ds_read_b128 v[152:155], v238 offset:2048
	ds_read_b128 v[156:159], v238 offset:3072
	s_add_u32 s38, s36, 0xfffc0080
	s_addc_u32 s39, s37, -1
	s_cmp_eq_u32 s58, 12
	s_cselect_b32 s41, s9, s39
	s_cselect_b32 s40, s27, s38
	s_cselect_b32 s39, s25, s57
	s_cselect_b32 s38, s35, s56
	v_lshl_add_u64 v[214:215], s[36:37], 0, v[198:199]
	s_add_i32 m0, s44, 0xc000
	ds_read_b128 v[160:163], v239
	ds_read_b128 v[164:167], v239 offset:1024
	ds_read_b128 v[168:171], v239 offset:2048
	ds_read_b128 v[172:175], v239 offset:3072
	ds_read_b128 v[176:179], v239 offset:4096
	ds_read_b128 v[180:183], v239 offset:5120
	ds_read_b128 v[206:209], v239 offset:6144
	ds_read_b128 v[210:213], v239 offset:7168
	global_load_lds_dwordx4 v[214:215], off
	v_lshl_add_u64 v[214:215], s[36:37], 0, v[200:201]
	s_add_i32 m0, s44, 0xe000
	s_nop 0
	global_load_lds_dwordx4 v[214:215], off
	s_waitcnt vmcnt(8)
	s_waitcnt lgkmcnt(0)
	s_barrier
	s_setprio 1
	s_waitcnt lgkmcnt(0)
	v_mfma_f32_16x16x32_bf16 v[132:135], v[120:123], v[160:163], v[132:135]
	v_mfma_f32_16x16x32_bf16 v[128:131], v[136:139], v[160:163], v[128:131]
	v_mfma_f32_16x16x32_bf16 v[108:111], v[120:123], v[168:171], v[108:111]
	v_mfma_f32_16x16x32_bf16 v[104:107], v[136:139], v[168:171], v[104:107]
	v_mfma_f32_16x16x32_bf16 v[92:95], v[120:123], v[176:179], v[92:95]
	v_mfma_f32_16x16x32_bf16 v[88:91], v[136:139], v[176:179], v[88:91]
	v_mfma_f32_16x16x32_bf16 v[76:79], v[120:123], v[206:209], v[76:79]
	v_mfma_f32_16x16x32_bf16 v[72:75], v[136:139], v[206:209], v[72:75]
	v_mfma_f32_16x16x32_bf16 v[132:135], v[124:127], v[164:167], v[132:135]
	v_mfma_f32_16x16x32_bf16 v[128:131], v[140:143], v[164:167], v[128:131]
	v_mfma_f32_16x16x32_bf16 v[108:111], v[124:127], v[172:175], v[108:111]
	v_mfma_f32_16x16x32_bf16 v[104:107], v[140:143], v[172:175], v[104:107]
	v_mfma_f32_16x16x32_bf16 v[92:95], v[124:127], v[180:183], v[92:95]
	v_mfma_f32_16x16x32_bf16 v[88:91], v[140:143], v[180:183], v[88:91]
	v_mfma_f32_16x16x32_bf16 v[76:79], v[124:127], v[210:213], v[76:79]
	v_mfma_f32_16x16x32_bf16 v[72:75], v[140:143], v[210:213], v[72:75]
	s_setprio 0
	s_setprio 1
	v_mfma_f32_16x16x32_bf16 v[116:119], v[144:147], v[160:163], v[116:119]
	v_mfma_f32_16x16x32_bf16 v[112:115], v[152:155], v[160:163], v[112:115]
	v_mfma_f32_16x16x32_bf16 v[100:103], v[144:147], v[168:171], v[100:103]
	v_mfma_f32_16x16x32_bf16 v[96:99], v[152:155], v[168:171], v[96:99]
	v_mfma_f32_16x16x32_bf16 v[84:87], v[144:147], v[176:179], v[84:87]
	v_mfma_f32_16x16x32_bf16 v[80:83], v[152:155], v[176:179], v[80:83]
	v_mfma_f32_16x16x32_bf16 v[68:71], v[144:147], v[206:209], v[68:71]
	v_mfma_f32_16x16x32_bf16 v[64:67], v[152:155], v[206:209], v[64:67]
	v_mfma_f32_16x16x32_bf16 v[116:119], v[148:151], v[164:167], v[116:119]
	v_mfma_f32_16x16x32_bf16 v[112:115], v[156:159], v[164:167], v[112:115]
	v_mfma_f32_16x16x32_bf16 v[100:103], v[148:151], v[172:175], v[100:103]
	v_mfma_f32_16x16x32_bf16 v[96:99], v[156:159], v[172:175], v[96:99]
	v_mfma_f32_16x16x32_bf16 v[84:87], v[148:151], v[180:183], v[84:87]
	v_mfma_f32_16x16x32_bf16 v[80:83], v[156:159], v[180:183], v[80:83]
	v_mfma_f32_16x16x32_bf16 v[68:71], v[148:151], v[210:213], v[68:71]
	v_mfma_f32_16x16x32_bf16 v[64:67], v[156:159], v[210:213], v[64:67]
	s_setprio 0
	s_barrier
	s_add_i32 s59, s53, s43
	v_lshl_add_u64 v[214:215], s[38:39], 0, v[188:189]
	s_mov_b32 m0, s59
	ds_read_b128 v[160:163], v239 offset:16384
	ds_read_b128 v[164:167], v239 offset:17408
	ds_read_b128 v[168:171], v239 offset:18432
	ds_read_b128 v[172:175], v239 offset:19456
	ds_read_b128 v[176:179], v239 offset:20480
	ds_read_b128 v[180:183], v239 offset:21504
	ds_read_b128 v[206:209], v239 offset:22528
	ds_read_b128 v[210:213], v239 offset:23552
	global_load_lds_dwordx4 v[214:215], off
	s_add_i32 m0, s59, 0x2000
	s_add_u32 s60, s38, 0x40000
	v_lshl_add_u64 v[216:217], s[38:39], 0, v[192:193]
	s_addc_u32 s61, s39, 0
	s_add_i32 s59, s54, s43
	global_load_lds_dwordx4 v[216:217], off
	v_lshl_add_u64 v[218:219], s[60:61], 0, v[188:189]
	s_mov_b32 m0, s59
	v_lshl_add_u64 v[220:221], s[40:41], 0, v[190:191]
	global_load_lds_dwordx4 v[218:219], off
	v_lshl_add_u64 v[218:219], s[60:61], 0, v[192:193]
	s_add_i32 m0, s59, 0x2000
	s_nop 0
	global_load_lds_dwordx4 v[218:219], off
	v_lshl_add_u64 v[218:219], s[40:41], 0, v[186:187]
	s_mov_b32 m0, s44
	s_nop 0
	global_load_lds_dwordx4 v[218:219], off
	s_mov_b32 m0, s45
	s_nop 0
	global_load_lds_dwordx4 v[220:221], off
	s_waitcnt vmcnt(8)
	s_waitcnt lgkmcnt(0)
	s_barrier
; #define PG8_STAGE(bufoff, gbase, voff) do { _Pragma("unroll") for (int _i = 0; _i < 2; ++_i) \
;         __builtin_amdgcn_global_load_lds((const unsigned*)((const char*)(gbase) + (voff)[_i]), (PG8_LAS unsigned*)(lds + (bufoff) + ldsw + _i * 8192), 16, 0, 0); } while (0)
; #define PG8_LDA(dst, b, h) do { _Pragma("unroll") for (int m = 0; m < 4; ++m) _Pragma("unroll") for (int k = 0; k < 2; ++k) dst[m][k] = *(const PG8_LAS bf16x8*)(lds + PG8_SA(b, h) + aoff + m * 2048 + k * 1024); } while (0)
; #define PG8_LDB(dst, b, h) do { _Pragma("unroll") for (int n = 0; n < 2; ++n) _Pragma("unroll") for (int k = 0; k < 2; ++k) dst[n][k] = *(const PG8_LAS bf16x8*)(lds + PG8_SB(b, h) + boff + n * 2048 + k * 1024); } while (0)
; #define PG8_MMA(ai, bj, At, Bt) do { __builtin_amdgcn_s_setprio(1); _Pragma("unroll") for (int m = 0; m < 4; ++m) _Pragma("unroll") for (int n = 0; n < 2; ++n) _Pragma("unroll") for (int k = 0; k < 2; ++k) \
;         acc[ai][bj][m][n] = __builtin_amdgcn_mfma_f32_16x16x32_bf16(Bt[n][k], At[m][k], acc[ai][bj][m][n], 0, 0, 0); __builtin_amdgcn_s_setprio(0); } while (0)
; #define PG8_WAIT_V(n) asm volatile("s_waitcnt vmcnt(" #n ")" ::: "memory")
; #define PG8_WAIT_L(n) asm volatile("s_waitcnt lgkmcnt(" #n ")" ::: "memory")
; #define PG8_BAR __builtin_amdgcn_s_barrier()
; #define PG8_SCHED __builtin_amdgcn_sched_barrier(0)
; template <class Epi, class Sched, bool ALIGN_EPI = false, bool SP2 = false>
; __device__ __forceinline__ void gemm_phase(PG8_LAS unsigned char* lds, const Gemm g, const Sched& S, const Epi& E) {
;     ...
;             PG8_WAIT_V(8); PG8_WAIT_L(0); PG8_BAR; PG8_MMA(1, 0, At, B0); PG8_MMA(1, 1, At, B1); PG8_BAR; PG8_SCHED;
;             PG8_LDB(B0, 1, 0); PG8_LDB(B1, 1, 1); PG8_SCHED; PG8_LDA(At, 1, 0); PG8_STAGE(PG8_SA(0, 1), a2 + hstepA, voffA);
;             PG8_WAIT_V(8); PG8_WAIT_L(0); PG8_BAR; PG8_MMA(0, 0, At, B0); PG8_MMA(0, 1, At, B1); PG8_BAR; PG8_SCHED;
	s_setprio 1
	s_waitcnt lgkmcnt(0)
	v_mfma_f32_16x16x32_bf16 v[60:63], v[120:123], v[160:163], v[60:63]
	v_mfma_f32_16x16x32_bf16 v[56:59], v[136:139], v[160:163], v[56:59]
	v_mfma_f32_16x16x32_bf16 v[44:47], v[120:123], v[168:171], v[44:47]
	v_mfma_f32_16x16x32_bf16 v[40:43], v[136:139], v[168:171], v[40:43]
	v_mfma_f32_16x16x32_bf16 v[28:31], v[120:123], v[176:179], v[28:31]
	v_mfma_f32_16x16x32_bf16 v[24:27], v[136:139], v[176:179], v[24:27]
	v_mfma_f32_16x16x32_bf16 v[12:15], v[120:123], v[206:209], v[12:15]
	v_mfma_f32_16x16x32_bf16 v[8:11], v[136:139], v[206:209], v[8:11]
	v_mfma_f32_16x16x32_bf16 v[60:63], v[124:127], v[164:167], v[60:63]
	v_mfma_f32_16x16x32_bf16 v[56:59], v[140:143], v[164:167], v[56:59]
	v_mfma_f32_16x16x32_bf16 v[44:47], v[124:127], v[172:175], v[44:47]
	v_mfma_f32_16x16x32_bf16 v[40:43], v[140:143], v[172:175], v[40:43]
	v_mfma_f32_16x16x32_bf16 v[28:31], v[124:127], v[180:183], v[28:31]
	v_mfma_f32_16x16x32_bf16 v[24:27], v[140:143], v[180:183], v[24:27]
	v_mfma_f32_16x16x32_bf16 v[12:15], v[124:127], v[210:213], v[12:15]
	v_mfma_f32_16x16x32_bf16 v[8:11], v[140:143], v[210:213], v[8:11]
	s_setprio 0
	s_setprio 1
	v_mfma_f32_16x16x32_bf16 v[52:55], v[144:147], v[160:163], v[52:55]
	v_mfma_f32_16x16x32_bf16 v[48:51], v[152:155], v[160:163], v[48:51]
	v_mfma_f32_16x16x32_bf16 v[36:39], v[144:147], v[168:171], v[36:39]
	v_mfma_f32_16x16x32_bf16 v[32:35], v[152:155], v[168:171], v[32:35]
	v_mfma_f32_16x16x32_bf16 v[20:23], v[144:147], v[176:179], v[20:23]
	v_mfma_f32_16x16x32_bf16 v[16:19], v[152:155], v[176:179], v[16:19]
	v_mfma_f32_16x16x32_bf16 v[4:7], v[144:147], v[206:209], v[4:7]
	v_mfma_f32_16x16x32_bf16 v[0:3], v[152:155], v[206:209], v[0:3]
	v_mfma_f32_16x16x32_bf16 v[52:55], v[148:151], v[164:167], v[52:55]
	v_mfma_f32_16x16x32_bf16 v[48:51], v[156:159], v[164:167], v[48:51]
	v_mfma_f32_16x16x32_bf16 v[36:39], v[148:151], v[172:175], v[36:39]
	v_mfma_f32_16x16x32_bf16 v[32:35], v[156:159], v[172:175], v[32:35]
	v_mfma_f32_16x16x32_bf16 v[20:23], v[148:151], v[180:183], v[20:23]
	v_mfma_f32_16x16x32_bf16 v[16:19], v[156:159], v[180:183], v[16:19]
	v_mfma_f32_16x16x32_bf16 v[4:7], v[148:151], v[210:213], v[4:7]
	v_mfma_f32_16x16x32_bf16 v[0:3], v[156:159], v[210:213], v[0:3]
	s_setprio 0
	s_barrier
	s_add_i32 s59, 0, 0x18000
	s_add_i32 s60, 0, 0x1c000
	v_add_u32_e32 v140, s59, v234
	v_add_u32_e32 v156, s60, v234
	ds_read_b128 v[120:123], v140
	ds_read_b128 v[124:127], v140 offset:1024
	ds_read_b128 v[136:139], v140 offset:2048
	ds_read_b128 v[140:143], v140 offset:3072
	ds_read_b128 v[144:147], v156
	ds_read_b128 v[148:151], v156 offset:1024
	ds_read_b128 v[152:155], v156 offset:2048
	ds_read_b128 v[156:159], v156 offset:3072
	s_add_u32 s40, s40, 0x40000
	s_addc_u32 s41, s41, 0
	s_mov_b32 m0, s46
	v_lshl_add_u64 v[222:223], s[40:41], 0, v[186:187]
	ds_read_b128 v[160:163], v239 offset:32768
	ds_read_b128 v[164:167], v239 offset:33792
	ds_read_b128 v[168:171], v239 offset:34816
	ds_read_b128 v[172:175], v239 offset:35840
	ds_read_b128 v[176:179], v239 offset:36864
	ds_read_b128 v[180:183], v239 offset:37888
	ds_read_b128 v[206:209], v239 offset:38912
	ds_read_b128 v[210:213], v239 offset:39936
	global_load_lds_dwordx4 v[222:223], off
	v_lshl_add_u64 v[222:223], s[40:41], 0, v[190:191]
	s_mov_b32 m0, s47
	s_nop 0
	global_load_lds_dwordx4 v[222:223], off
	s_waitcnt vmcnt(8)
	s_waitcnt lgkmcnt(0)
	s_barrier
	s_setprio 1
	s_waitcnt lgkmcnt(0)
	v_mfma_f32_16x16x32_bf16 v[132:135], v[120:123], v[160:163], v[132:135]
	v_mfma_f32_16x16x32_bf16 v[128:131], v[136:139], v[160:163], v[128:131]
	v_mfma_f32_16x16x32_bf16 v[108:111], v[120:123], v[168:171], v[108:111]
	v_mfma_f32_16x16x32_bf16 v[104:107], v[136:139], v[168:171], v[104:107]
	v_mfma_f32_16x16x32_bf16 v[92:95], v[120:123], v[176:179], v[92:95]
	v_mfma_f32_16x16x32_bf16 v[88:91], v[136:139], v[176:179], v[88:91]
	v_mfma_f32_16x16x32_bf16 v[76:79], v[120:123], v[206:209], v[76:79]
	v_mfma_f32_16x16x32_bf16 v[72:75], v[136:139], v[206:209], v[72:75]
	v_mfma_f32_16x16x32_bf16 v[132:135], v[124:127], v[164:167], v[132:135]
	v_mfma_f32_16x16x32_bf16 v[128:131], v[140:143], v[164:167], v[128:131]
	v_mfma_f32_16x16x32_bf16 v[108:111], v[124:127], v[172:175], v[108:111]
	v_mfma_f32_16x16x32_bf16 v[104:107], v[140:143], v[172:175], v[104:107]
	v_mfma_f32_16x16x32_bf16 v[92:95], v[124:127], v[180:183], v[92:95]
	v_mfma_f32_16x16x32_bf16 v[88:91], v[140:143], v[180:183], v[88:91]
	v_mfma_f32_16x16x32_bf16 v[76:79], v[124:127], v[210:213], v[76:79]
	v_mfma_f32_16x16x32_bf16 v[72:75], v[140:143], v[210:213], v[72:75]
	s_setprio 0
	s_setprio 1
	v_mfma_f32_16x16x32_bf16 v[116:119], v[144:147], v[160:163], v[116:119]
	v_mfma_f32_16x16x32_bf16 v[112:115], v[152:155], v[160:163], v[112:115]
	v_mfma_f32_16x16x32_bf16 v[100:103], v[144:147], v[168:171], v[100:103]
	v_mfma_f32_16x16x32_bf16 v[96:99], v[152:155], v[168:171], v[96:99]
	v_mfma_f32_16x16x32_bf16 v[84:87], v[144:147], v[176:179], v[84:87]
	v_mfma_f32_16x16x32_bf16 v[80:83], v[152:155], v[176:179], v[80:83]
	v_mfma_f32_16x16x32_bf16 v[68:71], v[144:147], v[206:209], v[68:71]
	v_mfma_f32_16x16x32_bf16 v[64:67], v[152:155], v[206:209], v[64:67]
	v_mfma_f32_16x16x32_bf16 v[116:119], v[148:151], v[164:167], v[116:119]
	v_mfma_f32_16x16x32_bf16 v[112:115], v[156:159], v[164:167], v[112:115]
	v_mfma_f32_16x16x32_bf16 v[100:103], v[148:151], v[172:175], v[100:103]
	v_mfma_f32_16x16x32_bf16 v[96:99], v[156:159], v[172:175], v[96:99]
	v_mfma_f32_16x16x32_bf16 v[84:87], v[148:151], v[180:183], v[84:87]
	v_mfma_f32_16x16x32_bf16 v[80:83], v[156:159], v[180:183], v[80:83]
	v_mfma_f32_16x16x32_bf16 v[68:71], v[148:151], v[210:213], v[68:71]
	v_mfma_f32_16x16x32_bf16 v[64:67], v[156:159], v[210:213], v[64:67]
	s_setprio 0
	s_barrier
; #define PG8_STAGE(bufoff, gbase, voff) do { _Pragma("unroll") for (int _i = 0; _i < 2; ++_i) \
;         __builtin_amdgcn_global_load_lds((const unsigned*)((const char*)(gbase) + (voff)[_i]), (PG8_LAS unsigned*)(lds + (bufoff) + ldsw + _i * 8192), 16, 0, 0); } while (0)
; #define PG8_LDA(dst, b, h) do { _Pragma("unroll") for (int m = 0; m < 4; ++m) _Pragma("unroll") for (int k = 0; k < 2; ++k) dst[m][k] = *(const PG8_LAS bf16x8*)(lds + PG8_SA(b, h) + aoff + m * 2048 + k * 1024); } while (0)
; #define PG8_MMA(ai, bj, At, Bt) do { __builtin_amdgcn_s_setprio(1); _Pragma("unroll") for (int m = 0; m < 4; ++m) _Pragma("unroll") for (int n = 0; n < 2; ++n) _Pragma("unroll") for (int k = 0; k < 2; ++k) \
;         acc[ai][bj][m][n] = __builtin_amdgcn_mfma_f32_16x16x32_bf16(Bt[n][k], At[m][k], acc[ai][bj][m][n], 0, 0, 0); __builtin_amdgcn_s_setprio(0); } while (0)
; #define PG8_WAIT_V(n) asm volatile("s_waitcnt vmcnt(" #n ")" ::: "memory")
; #define PG8_WAIT_L(n) asm volatile("s_waitcnt lgkmcnt(" #n ")" ::: "memory")
; #define PG8_BAR __builtin_amdgcn_s_barrier()
; #define PG8_SCHED __builtin_amdgcn_sched_barrier(0)
; template <class Epi, class Sched, bool ALIGN_EPI = false, bool SP2 = false>
; __device__ __forceinline__ void gemm_phase(PG8_LAS unsigned char* lds, const Gemm g, const Sched& S, const Epi& E) {
;     ...
;         for (int t = 0; t < nt; t += 2) {
;     ...
;             PG8_LDA(At, 1, 1); PG8_STAGE(PG8_SB(1, 0), b3, voffB); PG8_STAGE(PG8_SB(1, 1), b3 + hstepB, voffB); PG8_STAGE(PG8_SA(1, 0), a3, voffA);
;             PG8_WAIT_V(8); PG8_WAIT_L(0); PG8_BAR; PG8_MMA(1, 0, At, B0); PG8_MMA(1, 1, At, B1); PG8_BAR; PG8_SCHED;
	s_add_i32 s40, s59, s43
	v_lshl_add_u64 v[214:215], v[214:215], 0, s[20:21]
	s_mov_b32 m0, s40
	ds_read_b128 v[160:163], v239 offset:49152
	ds_read_b128 v[164:167], v239 offset:50176
	ds_read_b128 v[168:171], v239 offset:51200
	ds_read_b128 v[172:175], v239 offset:52224
	ds_read_b128 v[176:179], v239 offset:53248
	ds_read_b128 v[180:183], v239 offset:54272
	ds_read_b128 v[206:209], v239 offset:55296
	ds_read_b128 v[210:213], v239 offset:56320
	global_load_lds_dwordx4 v[214:215], off
	s_add_i32 m0, s40, 0x2000
	s_add_u32 s38, s38, 0x40080
	v_lshl_add_u64 v[214:215], v[216:217], 0, s[20:21]
	s_addc_u32 s39, s39, 0
	s_add_i32 s40, s60, s43
	global_load_lds_dwordx4 v[214:215], off
	v_lshl_add_u64 v[214:215], s[38:39], 0, v[188:189]
	s_mov_b32 m0, s40
	s_nop 0
	global_load_lds_dwordx4 v[214:215], off
	v_lshl_add_u64 v[214:215], s[38:39], 0, v[192:193]
	s_add_i32 m0, s40, 0x2000
	s_nop 0
	global_load_lds_dwordx4 v[214:215], off
	v_lshl_add_u64 v[214:215], v[218:219], 0, s[20:21]
	s_mov_b32 m0, s48
	s_nop 0
	global_load_lds_dwordx4 v[214:215], off
	v_lshl_add_u64 v[214:215], v[220:221], 0, s[20:21]
	s_mov_b32 m0, s49
	s_nop 0
	global_load_lds_dwordx4 v[214:215], off
	s_waitcnt vmcnt(8)
	s_waitcnt lgkmcnt(0)
	s_barrier
	s_setprio 1
	s_waitcnt lgkmcnt(0)
	v_mfma_f32_16x16x32_bf16 v[60:63], v[120:123], v[160:163], v[60:63]
	v_mfma_f32_16x16x32_bf16 v[56:59], v[136:139], v[160:163], v[56:59]
	v_mfma_f32_16x16x32_bf16 v[44:47], v[120:123], v[168:171], v[44:47]
	v_mfma_f32_16x16x32_bf16 v[40:43], v[136:139], v[168:171], v[40:43]
	v_mfma_f32_16x16x32_bf16 v[28:31], v[120:123], v[176:179], v[28:31]
	v_mfma_f32_16x16x32_bf16 v[24:27], v[136:139], v[176:179], v[24:27]
	v_mfma_f32_16x16x32_bf16 v[12:15], v[120:123], v[206:209], v[12:15]
	v_mfma_f32_16x16x32_bf16 v[8:11], v[136:139], v[206:209], v[8:11]
	v_mfma_f32_16x16x32_bf16 v[60:63], v[124:127], v[164:167], v[60:63]
	v_mfma_f32_16x16x32_bf16 v[56:59], v[140:143], v[164:167], v[56:59]
	v_mfma_f32_16x16x32_bf16 v[44:47], v[124:127], v[172:175], v[44:47]
	v_mfma_f32_16x16x32_bf16 v[40:43], v[140:143], v[172:175], v[40:43]
	v_mfma_f32_16x16x32_bf16 v[28:31], v[124:127], v[180:183], v[28:31]
	v_mfma_f32_16x16x32_bf16 v[24:27], v[140:143], v[180:183], v[24:27]
	v_mfma_f32_16x16x32_bf16 v[12:15], v[124:127], v[210:213], v[12:15]
	v_mfma_f32_16x16x32_bf16 v[8:11], v[140:143], v[210:213], v[8:11]
	s_setprio 0
	s_setprio 1
	v_mfma_f32_16x16x32_bf16 v[52:55], v[144:147], v[160:163], v[52:55]
	v_mfma_f32_16x16x32_bf16 v[48:51], v[152:155], v[160:163], v[48:51]
	v_mfma_f32_16x16x32_bf16 v[36:39], v[144:147], v[168:171], v[36:39]
	v_mfma_f32_16x16x32_bf16 v[32:35], v[152:155], v[168:171], v[32:35]
	v_mfma_f32_16x16x32_bf16 v[20:23], v[144:147], v[176:179], v[20:23]
	v_mfma_f32_16x16x32_bf16 v[16:19], v[152:155], v[176:179], v[16:19]
	v_mfma_f32_16x16x32_bf16 v[4:7], v[144:147], v[206:209], v[4:7]
	v_mfma_f32_16x16x32_bf16 v[0:3], v[152:155], v[206:209], v[0:3]
	v_mfma_f32_16x16x32_bf16 v[52:55], v[148:151], v[164:167], v[52:55]
	v_mfma_f32_16x16x32_bf16 v[48:51], v[156:159], v[164:167], v[48:51]
	v_mfma_f32_16x16x32_bf16 v[36:39], v[148:151], v[172:175], v[36:39]
	v_mfma_f32_16x16x32_bf16 v[32:35], v[156:159], v[172:175], v[32:35]
	v_mfma_f32_16x16x32_bf16 v[20:23], v[148:151], v[180:183], v[20:23]
	v_mfma_f32_16x16x32_bf16 v[16:19], v[156:159], v[180:183], v[16:19]
	v_mfma_f32_16x16x32_bf16 v[4:7], v[148:151], v[210:213], v[4:7]
	v_mfma_f32_16x16x32_bf16 v[0:3], v[156:159], v[210:213], v[0:3]
	s_setprio 0
	s_add_i32 s58, s58, 2
	s_add_u32 s36, s36, 0x100
	s_addc_u32 s37, s37, 0
	s_add_u32 s56, s56, 0x100
	s_addc_u32 s57, s57, 0
	s_cmp_gt_u32 s58, 13
	s_barrier
	s_cbranch_scc0 .LBB0_935
	s_and_b64 vcc, exec, s[22:23]
	s_cbranch_vccz .LBB0_938
	s_barrier

; #define PG8_STAGE(bufoff, gbase, voff) do { _Pragma("unroll") for (int _i = 0; _i < 2; ++_i) \
;         __builtin_amdgcn_global_load_lds((const unsigned*)((const char*)(gbase) + (voff)[_i]), (PG8_LAS unsigned*)(lds + (bufoff) + ldsw + _i * 8192), 16, 0, 0); } while (0)
; #define PG8_LDA(dst, b, h) do { _Pragma("unroll") for (int m = 0; m < 4; ++m) _Pragma("unroll") for (int k = 0; k < 2; ++k) dst[m][k] = *(const PG8_LAS bf16x8*)(lds + PG8_SA(b, h) + aoff + m * 2048 + k * 1024); } while (0)
; #define PG8_LDB(dst, b, h) do { _Pragma("unroll") for (int n = 0; n < 2; ++n) _Pragma("unroll") for (int k = 0; k < 2; ++k) dst[n][k] = *(const PG8_LAS bf16x8*)(lds + PG8_SB(b, h) + boff + n * 2048 + k * 1024); } while (0)
; #define PG8_MMA(ai, bj, At, Bt) do { __builtin_amdgcn_s_setprio(1); _Pragma("unroll") for (int m = 0; m < 4; ++m) _Pragma("unroll") for (int n = 0; n < 2; ++n) _Pragma("unroll") for (int k = 0; k < 2; ++k) \
;         acc[ai][bj][m][n] = __builtin_amdgcn_mfma_f32_16x16x32_bf16(Bt[n][k], At[m][k], acc[ai][bj][m][n], 0, 0, 0); __builtin_amdgcn_s_setprio(0); } while (0)
; #define PG8_WAIT_V(n) asm volatile("s_waitcnt vmcnt(" #n ")" ::: "memory")
; #define PG8_WAIT_L(n) asm volatile("s_waitcnt lgkmcnt(" #n ")" ::: "memory")
; #define PG8_BAR __builtin_amdgcn_s_barrier()
; template <class Epi, class Sched, bool ALIGN_EPI = false, bool SP2 = false>
; __device__ __forceinline__ void gemm_phase(PG8_LAS unsigned char* lds, const Gemm g, const Sched& S, const Epi& E) {
;     ...
;             const char* a1 = cA + (size_t)(t + 1) * kstep;
;             const char* a2 = last ? nA : cA + (size_t)(t + 2) * kstep; const char* b2 = last ? nB : cB + (size_t)(t + 2) * kstep;
;             const char* a3 = a2 + kstep; const char* b3 = b2 + kstep;
;             if (last && has_next) S.a_ready(nxt);
;             if constexpr (SP2) {
;             PG8_LDB(B0, 0, 0); PG8_LDB(B1, 0, 1); PG8_SCHED; PG8_LDA(At, 0, 0); PG8_STAGE(PG8_SA(1, 1), a1 + hstepA, voffA);
;             PG8_WAIT_V(8); PG8_WAIT_L(0); PG8_BAR; PG8_MMA(0, 0, At, B0); PG8_MMA(0, 1, At, B1); PG8_BAR; PG8_SCHED;
;             PG8_LDA(At, 0, 1); PG8_STAGE(PG8_SB(0, 0), b2, voffB); PG8_STAGE(PG8_SB(0, 1), b2 + hstepB, voffB); PG8_STAGE(PG8_SA(0, 0), a2, voffA);
;             PG8_WAIT_V(8); PG8_WAIT_L(0); PG8_BAR; PG8_MMA(1, 0, At, B0); PG8_MMA(1, 1, At, B1); PG8_BAR; PG8_SCHED;
.LBB0_1007:
	ds_read_b128 v[128:131], v176
	ds_read_b128 v[132:135], v176 offset:1024
	ds_read_b128 v[136:139], v176 offset:2048
	ds_read_b128 v[140:143], v176 offset:3072
	ds_read_b128 v[162:165], v177
	ds_read_b128 v[166:169], v177 offset:1024
	ds_read_b128 v[170:173], v177 offset:2048
	ds_read_b128 v[180:183], v177 offset:3072
	s_add_u32 s36, s34, 0xfffc0080
	s_addc_u32 s37, s35, -1
	s_cmp_eq_u32 s56, 12
	s_cselect_b32 s39, s25, s37
	s_cselect_b32 s38, s52, s36
	s_cselect_b32 s37, s23, s55
	s_cselect_b32 s36, s53, s54
	v_lshl_add_u64 v[218:219], s[34:35], 0, v[154:155]
	s_add_i32 m0, s41, 0xc000
	ds_read_b128 v[186:189], v178
	ds_read_b128 v[190:193], v178 offset:1024
	ds_read_b128 v[194:197], v178 offset:2048
	ds_read_b128 v[198:201], v178 offset:3072
	ds_read_b128 v[202:205], v178 offset:4096
	ds_read_b128 v[206:209], v178 offset:5120
	ds_read_b128 v[210:213], v178 offset:6144
	ds_read_b128 v[214:217], v178 offset:7168
	global_load_lds_dwordx4 v[218:219], off
	v_lshl_add_u64 v[218:219], s[34:35], 0, v[156:157]
	s_add_i32 m0, s41, 0xe000
	s_nop 0
	global_load_lds_dwordx4 v[218:219], off
	s_waitcnt vmcnt(8)
	s_waitcnt lgkmcnt(0)
	s_barrier
	s_setprio 1
	s_waitcnt lgkmcnt(0)
	v_mfma_f32_16x16x32_bf16 v[124:127], v[128:131], v[186:189], v[124:127]
	v_mfma_f32_16x16x32_bf16 v[120:123], v[136:139], v[186:189], v[120:123]
	v_mfma_f32_16x16x32_bf16 v[108:111], v[128:131], v[194:197], v[108:111]
	v_mfma_f32_16x16x32_bf16 v[104:107], v[136:139], v[194:197], v[104:107]
	v_mfma_f32_16x16x32_bf16 v[92:95], v[128:131], v[202:205], v[92:95]
	v_mfma_f32_16x16x32_bf16 v[88:91], v[136:139], v[202:205], v[88:91]
	v_mfma_f32_16x16x32_bf16 v[76:79], v[128:131], v[210:213], v[76:79]
	v_mfma_f32_16x16x32_bf16 v[72:75], v[136:139], v[210:213], v[72:75]
	v_mfma_f32_16x16x32_bf16 v[124:127], v[132:135], v[190:193], v[124:127]
	v_mfma_f32_16x16x32_bf16 v[120:123], v[140:143], v[190:193], v[120:123]
	v_mfma_f32_16x16x32_bf16 v[108:111], v[132:135], v[198:201], v[108:111]
	v_mfma_f32_16x16x32_bf16 v[104:107], v[140:143], v[198:201], v[104:107]
	v_mfma_f32_16x16x32_bf16 v[92:95], v[132:135], v[206:209], v[92:95]
	v_mfma_f32_16x16x32_bf16 v[88:91], v[140:143], v[206:209], v[88:91]
	v_mfma_f32_16x16x32_bf16 v[76:79], v[132:135], v[214:217], v[76:79]
	v_mfma_f32_16x16x32_bf16 v[72:75], v[140:143], v[214:217], v[72:75]
	s_setprio 0
	s_setprio 1
	v_mfma_f32_16x16x32_bf16 v[116:119], v[162:165], v[186:189], v[116:119]
	v_mfma_f32_16x16x32_bf16 v[112:115], v[170:173], v[186:189], v[112:115]
	v_mfma_f32_16x16x32_bf16 v[100:103], v[162:165], v[194:197], v[100:103]
	v_mfma_f32_16x16x32_bf16 v[96:99], v[170:173], v[194:197], v[96:99]
	v_mfma_f32_16x16x32_bf16 v[84:87], v[162:165], v[202:205], v[84:87]
	v_mfma_f32_16x16x32_bf16 v[80:83], v[170:173], v[202:205], v[80:83]
	v_mfma_f32_16x16x32_bf16 v[68:71], v[162:165], v[210:213], v[68:71]
	v_mfma_f32_16x16x32_bf16 v[64:67], v[170:173], v[210:213], v[64:67]
	v_mfma_f32_16x16x32_bf16 v[116:119], v[166:169], v[190:193], v[116:119]
	v_mfma_f32_16x16x32_bf16 v[112:115], v[180:183], v[190:193], v[112:115]
	v_mfma_f32_16x16x32_bf16 v[100:103], v[166:169], v[198:201], v[100:103]
	v_mfma_f32_16x16x32_bf16 v[96:99], v[180:183], v[198:201], v[96:99]
	v_mfma_f32_16x16x32_bf16 v[84:87], v[166:169], v[206:209], v[84:87]
	v_mfma_f32_16x16x32_bf16 v[80:83], v[180:183], v[206:209], v[80:83]
	v_mfma_f32_16x16x32_bf16 v[68:71], v[166:169], v[214:217], v[68:71]
	v_mfma_f32_16x16x32_bf16 v[64:67], v[180:183], v[214:217], v[64:67]
	s_setprio 0
	s_barrier
	s_add_i32 s57, s48, s40
	v_lshl_add_u64 v[218:219], s[36:37], 0, v[146:147]
	s_mov_b32 m0, s57
	ds_read_b128 v[186:189], v178 offset:16384
	ds_read_b128 v[190:193], v178 offset:17408
	ds_read_b128 v[194:197], v178 offset:18432
	ds_read_b128 v[198:201], v178 offset:19456
	ds_read_b128 v[202:205], v178 offset:20480
	ds_read_b128 v[206:209], v178 offset:21504
	ds_read_b128 v[210:213], v178 offset:22528
	ds_read_b128 v[214:217], v178 offset:23552
	global_load_lds_dwordx4 v[218:219], off
	s_add_i32 m0, s57, 0x2000
	s_add_u32 s58, s36, 0x40000
	v_lshl_add_u64 v[220:221], s[36:37], 0, v[150:151]
	s_addc_u32 s59, s37, 0
	s_add_i32 s57, s49, s40
	global_load_lds_dwordx4 v[220:221], off
	v_lshl_add_u64 v[222:223], s[58:59], 0, v[146:147]
	s_mov_b32 m0, s57
	v_lshl_add_u64 v[224:225], s[38:39], 0, v[148:149]
	global_load_lds_dwordx4 v[222:223], off
	v_lshl_add_u64 v[222:223], s[58:59], 0, v[150:151]
	s_add_i32 m0, s57, 0x2000
	s_nop 0
	global_load_lds_dwordx4 v[222:223], off
	v_lshl_add_u64 v[222:223], s[38:39], 0, v[144:145]
	s_mov_b32 m0, s41
	s_nop 0
	global_load_lds_dwordx4 v[222:223], off
	s_mov_b32 m0, s42
	s_nop 0
	global_load_lds_dwordx4 v[224:225], off
	s_waitcnt vmcnt(8)
	s_waitcnt lgkmcnt(0)
	s_barrier
; #define PG8_STAGE(bufoff, gbase, voff) do { _Pragma("unroll") for (int _i = 0; _i < 2; ++_i) \
;         __builtin_amdgcn_global_load_lds((const unsigned*)((const char*)(gbase) + (voff)[_i]), (PG8_LAS unsigned*)(lds + (bufoff) + ldsw + _i * 8192), 16, 0, 0); } while (0)
; #define PG8_LDA(dst, b, h) do { _Pragma("unroll") for (int m = 0; m < 4; ++m) _Pragma("unroll") for (int k = 0; k < 2; ++k) dst[m][k] = *(const PG8_LAS bf16x8*)(lds + PG8_SA(b, h) + aoff + m * 2048 + k * 1024); } while (0)
; #define PG8_LDB(dst, b, h) do { _Pragma("unroll") for (int n = 0; n < 2; ++n) _Pragma("unroll") for (int k = 0; k < 2; ++k) dst[n][k] = *(const PG8_LAS bf16x8*)(lds + PG8_SB(b, h) + boff + n * 2048 + k * 1024); } while (0)
; #define PG8_MMA(ai, bj, At, Bt) do { __builtin_amdgcn_s_setprio(1); _Pragma("unroll") for (int m = 0; m < 4; ++m) _Pragma("unroll") for (int n = 0; n < 2; ++n) _Pragma("unroll") for (int k = 0; k < 2; ++k) \
;         acc[ai][bj][m][n] = __builtin_amdgcn_mfma_f32_16x16x32_bf16(Bt[n][k], At[m][k], acc[ai][bj][m][n], 0, 0, 0); __builtin_amdgcn_s_setprio(0); } while (0)
; #define PG8_WAIT_V(n) asm volatile("s_waitcnt vmcnt(" #n ")" ::: "memory")
; #define PG8_WAIT_L(n) asm volatile("s_waitcnt lgkmcnt(" #n ")" ::: "memory")
; #define PG8_BAR __builtin_amdgcn_s_barrier()
; #define PG8_SCHED __builtin_amdgcn_sched_barrier(0)
; template <class Epi, class Sched, bool ALIGN_EPI = false, bool SP2 = false>
; __device__ __forceinline__ void gemm_phase(PG8_LAS unsigned char* lds, const Gemm g, const Sched& S, const Epi& E) {
;     ...
;             PG8_WAIT_V(8); PG8_WAIT_L(0); PG8_BAR; PG8_MMA(1, 0, At, B0); PG8_MMA(1, 1, At, B1); PG8_BAR; PG8_SCHED;
;             PG8_LDB(B0, 1, 0); PG8_LDB(B1, 1, 1); PG8_SCHED; PG8_LDA(At, 1, 0); PG8_STAGE(PG8_SA(0, 1), a2 + hstepA, voffA);
;             PG8_WAIT_V(8); PG8_WAIT_L(0); PG8_BAR; PG8_MMA(0, 0, At, B0); PG8_MMA(0, 1, At, B1); PG8_BAR; PG8_SCHED;
	s_setprio 1
	s_waitcnt lgkmcnt(0)
	v_mfma_f32_16x16x32_bf16 v[60:63], v[128:131], v[186:189], v[60:63]
	v_mfma_f32_16x16x32_bf16 v[56:59], v[136:139], v[186:189], v[56:59]
	v_mfma_f32_16x16x32_bf16 v[44:47], v[128:131], v[194:197], v[44:47]
	v_mfma_f32_16x16x32_bf16 v[40:43], v[136:139], v[194:197], v[40:43]
	v_mfma_f32_16x16x32_bf16 v[28:31], v[128:131], v[202:205], v[28:31]
	v_mfma_f32_16x16x32_bf16 v[24:27], v[136:139], v[202:205], v[24:27]
	v_mfma_f32_16x16x32_bf16 v[12:15], v[128:131], v[210:213], v[12:15]
	v_mfma_f32_16x16x32_bf16 v[8:11], v[136:139], v[210:213], v[8:11]
	v_mfma_f32_16x16x32_bf16 v[60:63], v[132:135], v[190:193], v[60:63]
	v_mfma_f32_16x16x32_bf16 v[56:59], v[140:143], v[190:193], v[56:59]
	v_mfma_f32_16x16x32_bf16 v[44:47], v[132:135], v[198:201], v[44:47]
	v_mfma_f32_16x16x32_bf16 v[40:43], v[140:143], v[198:201], v[40:43]
	v_mfma_f32_16x16x32_bf16 v[28:31], v[132:135], v[206:209], v[28:31]
	v_mfma_f32_16x16x32_bf16 v[24:27], v[140:143], v[206:209], v[24:27]
	v_mfma_f32_16x16x32_bf16 v[12:15], v[132:135], v[214:217], v[12:15]
	v_mfma_f32_16x16x32_bf16 v[8:11], v[140:143], v[214:217], v[8:11]
	s_setprio 0
	s_setprio 1
	v_mfma_f32_16x16x32_bf16 v[52:55], v[162:165], v[186:189], v[52:55]
	v_mfma_f32_16x16x32_bf16 v[48:51], v[170:173], v[186:189], v[48:51]
	v_mfma_f32_16x16x32_bf16 v[36:39], v[162:165], v[194:197], v[36:39]
	v_mfma_f32_16x16x32_bf16 v[32:35], v[170:173], v[194:197], v[32:35]
	v_mfma_f32_16x16x32_bf16 v[20:23], v[162:165], v[202:205], v[20:23]
	v_mfma_f32_16x16x32_bf16 v[16:19], v[170:173], v[202:205], v[16:19]
	v_mfma_f32_16x16x32_bf16 v[4:7], v[162:165], v[210:213], v[4:7]
	v_mfma_f32_16x16x32_bf16 v[0:3], v[170:173], v[210:213], v[0:3]
	v_mfma_f32_16x16x32_bf16 v[52:55], v[166:169], v[190:193], v[52:55]
	v_mfma_f32_16x16x32_bf16 v[48:51], v[180:183], v[190:193], v[48:51]
	v_mfma_f32_16x16x32_bf16 v[36:39], v[166:169], v[198:201], v[36:39]
	v_mfma_f32_16x16x32_bf16 v[32:35], v[180:183], v[198:201], v[32:35]
	v_mfma_f32_16x16x32_bf16 v[20:23], v[166:169], v[206:209], v[20:23]
	v_mfma_f32_16x16x32_bf16 v[16:19], v[180:183], v[206:209], v[16:19]
	v_mfma_f32_16x16x32_bf16 v[4:7], v[166:169], v[214:217], v[4:7]
	v_mfma_f32_16x16x32_bf16 v[0:3], v[180:183], v[214:217], v[0:3]
	s_setprio 0
	s_barrier
	s_add_i32 s57, 0, 0x18000
	s_add_i32 s58, 0, 0x1c000
	v_add_u32_e32 v140, s57, v175
	v_add_u32_e32 v179, s58, v175
	ds_read_b128 v[128:131], v140
	ds_read_b128 v[132:135], v140 offset:1024
	ds_read_b128 v[136:139], v140 offset:2048
	ds_read_b128 v[140:143], v140 offset:3072
	ds_read_b128 v[162:165], v179
	ds_read_b128 v[166:169], v179 offset:1024
	ds_read_b128 v[170:173], v179 offset:2048
	ds_read_b128 v[180:183], v179 offset:3072
	s_add_u32 s38, s38, 0x40000
	s_addc_u32 s39, s39, 0
	s_mov_b32 m0, s43
	v_lshl_add_u64 v[226:227], s[38:39], 0, v[144:145]
	ds_read_b128 v[186:189], v178 offset:32768
	ds_read_b128 v[190:193], v178 offset:33792
	ds_read_b128 v[194:197], v178 offset:34816
	ds_read_b128 v[198:201], v178 offset:35840
	ds_read_b128 v[202:205], v178 offset:36864
	ds_read_b128 v[206:209], v178 offset:37888
	ds_read_b128 v[210:213], v178 offset:38912
	ds_read_b128 v[214:217], v178 offset:39936
	global_load_lds_dwordx4 v[226:227], off
	v_lshl_add_u64 v[226:227], s[38:39], 0, v[148:149]
	s_mov_b32 m0, s44
	s_nop 0
	global_load_lds_dwordx4 v[226:227], off
	s_waitcnt vmcnt(8)
	s_waitcnt lgkmcnt(0)
	s_barrier
	s_setprio 1
	s_waitcnt lgkmcnt(0)
	v_mfma_f32_16x16x32_bf16 v[124:127], v[128:131], v[186:189], v[124:127]
	v_mfma_f32_16x16x32_bf16 v[120:123], v[136:139], v[186:189], v[120:123]
	v_mfma_f32_16x16x32_bf16 v[108:111], v[128:131], v[194:197], v[108:111]
	v_mfma_f32_16x16x32_bf16 v[104:107], v[136:139], v[194:197], v[104:107]
	v_mfma_f32_16x16x32_bf16 v[92:95], v[128:131], v[202:205], v[92:95]
	v_mfma_f32_16x16x32_bf16 v[88:91], v[136:139], v[202:205], v[88:91]
	v_mfma_f32_16x16x32_bf16 v[76:79], v[128:131], v[210:213], v[76:79]
	v_mfma_f32_16x16x32_bf16 v[72:75], v[136:139], v[210:213], v[72:75]
	v_mfma_f32_16x16x32_bf16 v[124:127], v[132:135], v[190:193], v[124:127]
	v_mfma_f32_16x16x32_bf16 v[120:123], v[140:143], v[190:193], v[120:123]
	v_mfma_f32_16x16x32_bf16 v[108:111], v[132:135], v[198:201], v[108:111]
	v_mfma_f32_16x16x32_bf16 v[104:107], v[140:143], v[198:201], v[104:107]
	v_mfma_f32_16x16x32_bf16 v[92:95], v[132:135], v[206:209], v[92:95]
	v_mfma_f32_16x16x32_bf16 v[88:91], v[140:143], v[206:209], v[88:91]
	v_mfma_f32_16x16x32_bf16 v[76:79], v[132:135], v[214:217], v[76:79]
	v_mfma_f32_16x16x32_bf16 v[72:75], v[140:143], v[214:217], v[72:75]
	s_setprio 0
	s_setprio 1
	v_mfma_f32_16x16x32_bf16 v[116:119], v[162:165], v[186:189], v[116:119]
	v_mfma_f32_16x16x32_bf16 v[112:115], v[170:173], v[186:189], v[112:115]
	v_mfma_f32_16x16x32_bf16 v[100:103], v[162:165], v[194:197], v[100:103]
	v_mfma_f32_16x16x32_bf16 v[96:99], v[170:173], v[194:197], v[96:99]
	v_mfma_f32_16x16x32_bf16 v[84:87], v[162:165], v[202:205], v[84:87]
	v_mfma_f32_16x16x32_bf16 v[80:83], v[170:173], v[202:205], v[80:83]
	v_mfma_f32_16x16x32_bf16 v[68:71], v[162:165], v[210:213], v[68:71]
	v_mfma_f32_16x16x32_bf16 v[64:67], v[170:173], v[210:213], v[64:67]
	v_mfma_f32_16x16x32_bf16 v[116:119], v[166:169], v[190:193], v[116:119]
	v_mfma_f32_16x16x32_bf16 v[112:115], v[180:183], v[190:193], v[112:115]
	v_mfma_f32_16x16x32_bf16 v[100:103], v[166:169], v[198:201], v[100:103]
	v_mfma_f32_16x16x32_bf16 v[96:99], v[180:183], v[198:201], v[96:99]
	v_mfma_f32_16x16x32_bf16 v[84:87], v[166:169], v[206:209], v[84:87]
	v_mfma_f32_16x16x32_bf16 v[80:83], v[180:183], v[206:209], v[80:83]
	v_mfma_f32_16x16x32_bf16 v[68:71], v[166:169], v[214:217], v[68:71]
	v_mfma_f32_16x16x32_bf16 v[64:67], v[180:183], v[214:217], v[64:67]
	s_setprio 0
	s_barrier
; #define PG8_STAGE(bufoff, gbase, voff) do { _Pragma("unroll") for (int _i = 0; _i < 2; ++_i) \
;         __builtin_amdgcn_global_load_lds((const unsigned*)((const char*)(gbase) + (voff)[_i]), (PG8_LAS unsigned*)(lds + (bufoff) + ldsw + _i * 8192), 16, 0, 0); } while (0)
; #define PG8_LDA(dst, b, h) do { _Pragma("unroll") for (int m = 0; m < 4; ++m) _Pragma("unroll") for (int k = 0; k < 2; ++k) dst[m][k] = *(const PG8_LAS bf16x8*)(lds + PG8_SA(b, h) + aoff + m * 2048 + k * 1024); } while (0)
; #define PG8_MMA(ai, bj, At, Bt) do { __builtin_amdgcn_s_setprio(1); _Pragma("unroll") for (int m = 0; m < 4; ++m) _Pragma("unroll") for (int n = 0; n < 2; ++n) _Pragma("unroll") for (int k = 0; k < 2; ++k) \
;         acc[ai][bj][m][n] = __builtin_amdgcn_mfma_f32_16x16x32_bf16(Bt[n][k], At[m][k], acc[ai][bj][m][n], 0, 0, 0); __builtin_amdgcn_s_setprio(0); } while (0)
; #define PG8_WAIT_V(n) asm volatile("s_waitcnt vmcnt(" #n ")" ::: "memory")
; #define PG8_WAIT_L(n) asm volatile("s_waitcnt lgkmcnt(" #n ")" ::: "memory")
; #define PG8_BAR __builtin_amdgcn_s_barrier()
; #define PG8_SCHED __builtin_amdgcn_sched_barrier(0)
; template <class Epi, class Sched, bool ALIGN_EPI = false, bool SP2 = false>
; __device__ __forceinline__ void gemm_phase(PG8_LAS unsigned char* lds, const Gemm g, const Sched& S, const Epi& E) {
;     ...
;         for (int t = 0; t < nt; t += 2) {
;     ...
;             PG8_LDA(At, 1, 1); PG8_STAGE(PG8_SB(1, 0), b3, voffB); PG8_STAGE(PG8_SB(1, 1), b3 + hstepB, voffB); PG8_STAGE(PG8_SA(1, 0), a3, voffA);
;             PG8_WAIT_V(8); PG8_WAIT_L(0); PG8_BAR; PG8_MMA(1, 0, At, B0); PG8_MMA(1, 1, At, B1); PG8_BAR; PG8_SCHED;
	s_add_i32 s38, s57, s40
	v_lshl_add_u64 v[218:219], v[218:219], 0, s[12:13]
	s_mov_b32 m0, s38
	ds_read_b128 v[186:189], v178 offset:49152
	ds_read_b128 v[190:193], v178 offset:50176
	ds_read_b128 v[194:197], v178 offset:51200
	ds_read_b128 v[198:201], v178 offset:52224
	ds_read_b128 v[202:205], v178 offset:53248
	ds_read_b128 v[206:209], v178 offset:54272
	ds_read_b128 v[210:213], v178 offset:55296
	ds_read_b128 v[214:217], v178 offset:56320
	global_load_lds_dwordx4 v[218:219], off
	s_add_i32 m0, s38, 0x2000
	s_add_u32 s36, s36, 0x40080
	v_lshl_add_u64 v[218:219], v[220:221], 0, s[12:13]
	s_addc_u32 s37, s37, 0
	s_add_i32 s38, s58, s40
	global_load_lds_dwordx4 v[218:219], off
	v_lshl_add_u64 v[218:219], s[36:37], 0, v[146:147]
	s_mov_b32 m0, s38
	s_nop 0
	global_load_lds_dwordx4 v[218:219], off
	v_lshl_add_u64 v[218:219], s[36:37], 0, v[150:151]
	s_add_i32 m0, s38, 0x2000
	s_nop 0
	global_load_lds_dwordx4 v[218:219], off
	v_lshl_add_u64 v[218:219], v[222:223], 0, s[12:13]
	s_mov_b32 m0, s45
	s_nop 0
	global_load_lds_dwordx4 v[218:219], off
	v_lshl_add_u64 v[218:219], v[224:225], 0, s[12:13]
	s_mov_b32 m0, s46
	s_nop 0
	global_load_lds_dwordx4 v[218:219], off
	s_waitcnt vmcnt(8)
	s_waitcnt lgkmcnt(0)
	s_barrier
	s_setprio 1
	s_waitcnt lgkmcnt(0)
	v_mfma_f32_16x16x32_bf16 v[60:63], v[128:131], v[186:189], v[60:63]
	v_mfma_f32_16x16x32_bf16 v[56:59], v[136:139], v[186:189], v[56:59]
	v_mfma_f32_16x16x32_bf16 v[44:47], v[128:131], v[194:197], v[44:47]
	v_mfma_f32_16x16x32_bf16 v[40:43], v[136:139], v[194:197], v[40:43]
	v_mfma_f32_16x16x32_bf16 v[28:31], v[128:131], v[202:205], v[28:31]
	v_mfma_f32_16x16x32_bf16 v[24:27], v[136:139], v[202:205], v[24:27]
	v_mfma_f32_16x16x32_bf16 v[12:15], v[128:131], v[210:213], v[12:15]
	v_mfma_f32_16x16x32_bf16 v[8:11], v[136:139], v[210:213], v[8:11]
	v_mfma_f32_16x16x32_bf16 v[60:63], v[132:135], v[190:193], v[60:63]
	v_mfma_f32_16x16x32_bf16 v[56:59], v[140:143], v[190:193], v[56:59]
	v_mfma_f32_16x16x32_bf16 v[44:47], v[132:135], v[198:201], v[44:47]
	v_mfma_f32_16x16x32_bf16 v[40:43], v[140:143], v[198:201], v[40:43]
	v_mfma_f32_16x16x32_bf16 v[28:31], v[132:135], v[206:209], v[28:31]
	v_mfma_f32_16x16x32_bf16 v[24:27], v[140:143], v[206:209], v[24:27]
	v_mfma_f32_16x16x32_bf16 v[12:15], v[132:135], v[214:217], v[12:15]
	v_mfma_f32_16x16x32_bf16 v[8:11], v[140:143], v[214:217], v[8:11]
	s_setprio 0
	s_setprio 1
	v_mfma_f32_16x16x32_bf16 v[52:55], v[162:165], v[186:189], v[52:55]
	v_mfma_f32_16x16x32_bf16 v[48:51], v[170:173], v[186:189], v[48:51]
	v_mfma_f32_16x16x32_bf16 v[36:39], v[162:165], v[194:197], v[36:39]
	v_mfma_f32_16x16x32_bf16 v[32:35], v[170:173], v[194:197], v[32:35]
	v_mfma_f32_16x16x32_bf16 v[20:23], v[162:165], v[202:205], v[20:23]
	v_mfma_f32_16x16x32_bf16 v[16:19], v[170:173], v[202:205], v[16:19]
	v_mfma_f32_16x16x32_bf16 v[4:7], v[162:165], v[210:213], v[4:7]
	v_mfma_f32_16x16x32_bf16 v[0:3], v[170:173], v[210:213], v[0:3]
	v_mfma_f32_16x16x32_bf16 v[52:55], v[166:169], v[190:193], v[52:55]
	v_mfma_f32_16x16x32_bf16 v[48:51], v[180:183], v[190:193], v[48:51]
	v_mfma_f32_16x16x32_bf16 v[36:39], v[166:169], v[198:201], v[36:39]
	v_mfma_f32_16x16x32_bf16 v[32:35], v[180:183], v[198:201], v[32:35]
	v_mfma_f32_16x16x32_bf16 v[20:23], v[166:169], v[206:209], v[20:23]
	v_mfma_f32_16x16x32_bf16 v[16:19], v[180:183], v[206:209], v[16:19]
	v_mfma_f32_16x16x32_bf16 v[4:7], v[166:169], v[214:217], v[4:7]
	v_mfma_f32_16x16x32_bf16 v[0:3], v[180:183], v[214:217], v[0:3]
	s_setprio 0
	s_add_i32 s56, s56, 2
	s_add_u32 s34, s34, 0x100
	s_addc_u32 s35, s35, 0
	s_add_u32 s54, s54, 0x100
	s_addc_u32 s55, s55, 0
	s_cmp_gt_u32 s56, 13
	s_barrier
	s_cbranch_scc0 .LBB0_1007
	s_and_b64 vcc, exec, s[16:17]
	s_cbranch_vccz .LBB0_1010
	s_barrier

; #define PG8_STAGE(bufoff, gbase, voff) do { _Pragma("unroll") for (int _i = 0; _i < 2; ++_i) \
;         __builtin_amdgcn_global_load_lds((const unsigned*)((const char*)(gbase) + (voff)[_i]), (PG8_LAS unsigned*)(lds + (bufoff) + ldsw + _i * 8192), 16, 0, 0); } while (0)
; #define PG8_LDA(dst, b, h) do { _Pragma("unroll") for (int m = 0; m < 4; ++m) _Pragma("unroll") for (int k = 0; k < 2; ++k) dst[m][k] = *(const PG8_LAS bf16x8*)(lds + PG8_SA(b, h) + aoff + m * 2048 + k * 1024); } while (0)
; #define PG8_LDB(dst, b, h) do { _Pragma("unroll") for (int n = 0; n < 2; ++n) _Pragma("unroll") for (int k = 0; k < 2; ++k) dst[n][k] = *(const PG8_LAS bf16x8*)(lds + PG8_SB(b, h) + boff + n * 2048 + k * 1024); } while (0)
; #define PG8_MMA(ai, bj, At, Bt) do { __builtin_amdgcn_s_setprio(1); _Pragma("unroll") for (int m = 0; m < 4; ++m) _Pragma("unroll") for (int n = 0; n < 2; ++n) _Pragma("unroll") for (int k = 0; k < 2; ++k) \
;         acc[ai][bj][m][n] = __builtin_amdgcn_mfma_f32_16x16x32_bf16(Bt[n][k], At[m][k], acc[ai][bj][m][n], 0, 0, 0); __builtin_amdgcn_s_setprio(0); } while (0)
; #define PG8_WAIT_V(n) asm volatile("s_waitcnt vmcnt(" #n ")" ::: "memory")
; #define PG8_WAIT_L(n) asm volatile("s_waitcnt lgkmcnt(" #n ")" ::: "memory")
; #define PG8_BAR __builtin_amdgcn_s_barrier()
; #define PG8_SCHED __builtin_amdgcn_sched_barrier(0)
; template <class Epi, class Sched, bool ALIGN_EPI = false, bool SP2 = false>
; __device__ __forceinline__ void gemm_phase(PG8_LAS unsigned char* lds, const Gemm g, const Sched& S, const Epi& E) {
;     ...
;             PG8_LDB(B0, 0, 0); PG8_LDB(B1, 0, 1); PG8_SCHED; PG8_LDA(At, 0, 0); PG8_STAGE(PG8_SA(1, 1), a1 + hstepA, voffA);
;             PG8_WAIT_V(8); PG8_WAIT_L(0); PG8_BAR; PG8_MMA(0, 0, At, B0); PG8_MMA(0, 1, At, B1); PG8_BAR; PG8_SCHED;
;             PG8_LDA(At, 0, 1); PG8_STAGE(PG8_SB(0, 0), b2, voffB); PG8_STAGE(PG8_SB(0, 1), b2 + hstepB, voffB); PG8_STAGE(PG8_SA(0, 0), a2, voffA);
;             PG8_WAIT_V(8); PG8_WAIT_L(0); PG8_BAR; PG8_MMA(1, 0, At, B0); PG8_MMA(1, 1, At, B1); PG8_BAR; PG8_SCHED;
.LBB0_1061:
	ds_read_b128 v[128:131], v199
	ds_read_b128 v[132:135], v199 offset:1024
	ds_read_b128 v[136:139], v199 offset:2048
	ds_read_b128 v[140:143], v199 offset:3072
	ds_read_b128 v[144:147], v200
	ds_read_b128 v[148:151], v200 offset:1024
	ds_read_b128 v[152:155], v200 offset:2048
	ds_read_b128 v[156:159], v200 offset:3072
	s_add_u32 s20, s18, 0xfff00080
	s_addc_u32 s21, s19, -1
	s_cmp_eq_u32 s45, 60
	s_cselect_b32 s23, s11, s21
	s_cselect_b32 s22, s41, s20
	s_cselect_b32 s21, s9, s44
	s_cselect_b32 s20, s42, s43
	v_lshl_add_u64 v[196:197], s[18:19], 0, v[180:181]
	s_add_i32 m0, s17, 0xc000
	ds_read_b128 v[160:163], v201
	ds_read_b128 v[164:167], v201 offset:1024
	ds_read_b128 v[188:191], v201 offset:2048
	ds_read_b128 v[192:195], v201 offset:3072
	ds_read_b128 v[202:205], v201 offset:4096
	ds_read_b128 v[206:209], v201 offset:5120
	ds_read_b128 v[210:213], v201 offset:6144
	ds_read_b128 v[214:217], v201 offset:7168
	global_load_lds_dwordx4 v[196:197], off
	v_lshl_add_u64 v[196:197], s[18:19], 0, v[182:183]
	s_add_i32 m0, s17, 0xe000
	s_nop 0
	global_load_lds_dwordx4 v[196:197], off
	s_waitcnt vmcnt(8)
	s_waitcnt lgkmcnt(0)
	s_barrier
	s_setprio 1
	s_waitcnt lgkmcnt(0)
	v_mfma_f32_16x16x32_bf16 v[124:127], v[128:131], v[160:163], v[124:127]
	v_mfma_f32_16x16x32_bf16 v[120:123], v[136:139], v[160:163], v[120:123]
	v_mfma_f32_16x16x32_bf16 v[112:115], v[128:131], v[188:191], v[112:115]
	v_mfma_f32_16x16x32_bf16 v[104:107], v[136:139], v[188:191], v[104:107]
	v_mfma_f32_16x16x32_bf16 v[96:99], v[128:131], v[202:205], v[96:99]
	v_mfma_f32_16x16x32_bf16 v[88:91], v[136:139], v[202:205], v[88:91]
	v_mfma_f32_16x16x32_bf16 v[80:83], v[128:131], v[210:213], v[80:83]
	v_mfma_f32_16x16x32_bf16 v[72:75], v[136:139], v[210:213], v[72:75]
	v_mfma_f32_16x16x32_bf16 v[124:127], v[132:135], v[164:167], v[124:127]
	v_mfma_f32_16x16x32_bf16 v[120:123], v[140:143], v[164:167], v[120:123]
	v_mfma_f32_16x16x32_bf16 v[112:115], v[132:135], v[192:195], v[112:115]
	v_mfma_f32_16x16x32_bf16 v[104:107], v[140:143], v[192:195], v[104:107]
	v_mfma_f32_16x16x32_bf16 v[96:99], v[132:135], v[206:209], v[96:99]
	v_mfma_f32_16x16x32_bf16 v[88:91], v[140:143], v[206:209], v[88:91]
	v_mfma_f32_16x16x32_bf16 v[80:83], v[132:135], v[214:217], v[80:83]
	v_mfma_f32_16x16x32_bf16 v[72:75], v[140:143], v[214:217], v[72:75]
	s_setprio 0
	s_setprio 1
	v_mfma_f32_16x16x32_bf16 v[116:119], v[144:147], v[160:163], v[116:119]
	v_mfma_f32_16x16x32_bf16 v[108:111], v[152:155], v[160:163], v[108:111]
	v_mfma_f32_16x16x32_bf16 v[100:103], v[144:147], v[188:191], v[100:103]
	v_mfma_f32_16x16x32_bf16 v[92:95], v[152:155], v[188:191], v[92:95]
	v_mfma_f32_16x16x32_bf16 v[84:87], v[144:147], v[202:205], v[84:87]
	v_mfma_f32_16x16x32_bf16 v[76:79], v[152:155], v[202:205], v[76:79]
	v_mfma_f32_16x16x32_bf16 v[68:71], v[144:147], v[210:213], v[68:71]
	v_mfma_f32_16x16x32_bf16 v[64:67], v[152:155], v[210:213], v[64:67]
	v_mfma_f32_16x16x32_bf16 v[116:119], v[148:151], v[164:167], v[116:119]
	v_mfma_f32_16x16x32_bf16 v[108:111], v[156:159], v[164:167], v[108:111]
	v_mfma_f32_16x16x32_bf16 v[100:103], v[148:151], v[192:195], v[100:103]
	v_mfma_f32_16x16x32_bf16 v[92:95], v[156:159], v[192:195], v[92:95]
	v_mfma_f32_16x16x32_bf16 v[84:87], v[148:151], v[206:209], v[84:87]
	v_mfma_f32_16x16x32_bf16 v[76:79], v[156:159], v[206:209], v[76:79]
	v_mfma_f32_16x16x32_bf16 v[68:71], v[148:151], v[214:217], v[68:71]
	v_mfma_f32_16x16x32_bf16 v[64:67], v[156:159], v[214:217], v[64:67]
	s_setprio 0
	s_barrier
	s_add_i32 s46, s38, s29
	v_lshl_add_u64 v[196:197], s[20:21], 0, v[170:171]
	s_mov_b32 m0, s46
	ds_read_b128 v[160:163], v201 offset:16384
	ds_read_b128 v[164:167], v201 offset:17408
	ds_read_b128 v[188:191], v201 offset:18432
	ds_read_b128 v[192:195], v201 offset:19456
	ds_read_b128 v[202:205], v201 offset:20480
	ds_read_b128 v[206:209], v201 offset:21504
	ds_read_b128 v[210:213], v201 offset:22528
	ds_read_b128 v[214:217], v201 offset:23552
	global_load_lds_dwordx4 v[196:197], off
	s_add_i32 m0, s46, 0x2000
	s_add_u32 s46, s20, 0x100000
	v_lshl_add_u64 v[218:219], s[20:21], 0, v[174:175]
	s_addc_u32 s47, s21, 0
	s_add_i32 s48, s39, s29
	global_load_lds_dwordx4 v[218:219], off
	v_lshl_add_u64 v[220:221], s[46:47], 0, v[170:171]
	s_mov_b32 m0, s48
	v_lshl_add_u64 v[222:223], s[22:23], 0, v[172:173]
	global_load_lds_dwordx4 v[220:221], off
	v_lshl_add_u64 v[220:221], s[46:47], 0, v[174:175]
	s_add_i32 m0, s48, 0x2000
	s_nop 0
	global_load_lds_dwordx4 v[220:221], off
	v_lshl_add_u64 v[220:221], s[22:23], 0, v[168:169]
	s_mov_b32 m0, s17
	s_nop 0
	global_load_lds_dwordx4 v[220:221], off
	s_mov_b32 m0, s30
	s_nop 0
	global_load_lds_dwordx4 v[222:223], off
	s_waitcnt vmcnt(8)
	s_waitcnt lgkmcnt(0)
	s_barrier
; #define PG8_STAGE(bufoff, gbase, voff) do { _Pragma("unroll") for (int _i = 0; _i < 2; ++_i) \
;         __builtin_amdgcn_global_load_lds((const unsigned*)((const char*)(gbase) + (voff)[_i]), (PG8_LAS unsigned*)(lds + (bufoff) + ldsw + _i * 8192), 16, 0, 0); } while (0)
; #define PG8_LDA(dst, b, h) do { _Pragma("unroll") for (int m = 0; m < 4; ++m) _Pragma("unroll") for (int k = 0; k < 2; ++k) dst[m][k] = *(const PG8_LAS bf16x8*)(lds + PG8_SA(b, h) + aoff + m * 2048 + k * 1024); } while (0)
; #define PG8_LDB(dst, b, h) do { _Pragma("unroll") for (int n = 0; n < 2; ++n) _Pragma("unroll") for (int k = 0; k < 2; ++k) dst[n][k] = *(const PG8_LAS bf16x8*)(lds + PG8_SB(b, h) + boff + n * 2048 + k * 1024); } while (0)
; #define PG8_MMA(ai, bj, At, Bt) do { __builtin_amdgcn_s_setprio(1); _Pragma("unroll") for (int m = 0; m < 4; ++m) _Pragma("unroll") for (int n = 0; n < 2; ++n) _Pragma("unroll") for (int k = 0; k < 2; ++k) \
;         acc[ai][bj][m][n] = __builtin_amdgcn_mfma_f32_16x16x32_bf16(Bt[n][k], At[m][k], acc[ai][bj][m][n], 0, 0, 0); __builtin_amdgcn_s_setprio(0); } while (0)
; #define PG8_WAIT_V(n) asm volatile("s_waitcnt vmcnt(" #n ")" ::: "memory")
; #define PG8_WAIT_L(n) asm volatile("s_waitcnt lgkmcnt(" #n ")" ::: "memory")
; #define PG8_BAR __builtin_amdgcn_s_barrier()
; #define PG8_SCHED __builtin_amdgcn_sched_barrier(0)
; template <class Epi, class Sched, bool ALIGN_EPI = false, bool SP2 = false>
; __device__ __forceinline__ void gemm_phase(PG8_LAS unsigned char* lds, const Gemm g, const Sched& S, const Epi& E) {
;     ...
;             PG8_WAIT_V(8); PG8_WAIT_L(0); PG8_BAR; PG8_MMA(1, 0, At, B0); PG8_MMA(1, 1, At, B1); PG8_BAR; PG8_SCHED;
;             PG8_LDB(B0, 1, 0); PG8_LDB(B1, 1, 1); PG8_SCHED; PG8_LDA(At, 1, 0); PG8_STAGE(PG8_SA(0, 1), a2 + hstepA, voffA);
;             PG8_WAIT_V(8); PG8_WAIT_L(0); PG8_BAR; PG8_MMA(0, 0, At, B0); PG8_MMA(0, 1, At, B1); PG8_BAR; PG8_SCHED;
	s_setprio 1
	s_waitcnt lgkmcnt(0)
	v_mfma_f32_16x16x32_bf16 v[60:63], v[128:131], v[160:163], v[60:63]
	v_mfma_f32_16x16x32_bf16 v[56:59], v[136:139], v[160:163], v[56:59]
	v_mfma_f32_16x16x32_bf16 v[48:51], v[128:131], v[188:191], v[48:51]
	v_mfma_f32_16x16x32_bf16 v[40:43], v[136:139], v[188:191], v[40:43]
	v_mfma_f32_16x16x32_bf16 v[32:35], v[128:131], v[202:205], v[32:35]
	v_mfma_f32_16x16x32_bf16 v[24:27], v[136:139], v[202:205], v[24:27]
	v_mfma_f32_16x16x32_bf16 v[16:19], v[128:131], v[210:213], v[16:19]
	v_mfma_f32_16x16x32_bf16 v[8:11], v[136:139], v[210:213], v[8:11]
	v_mfma_f32_16x16x32_bf16 v[60:63], v[132:135], v[164:167], v[60:63]
	v_mfma_f32_16x16x32_bf16 v[56:59], v[140:143], v[164:167], v[56:59]
	v_mfma_f32_16x16x32_bf16 v[48:51], v[132:135], v[192:195], v[48:51]
	v_mfma_f32_16x16x32_bf16 v[40:43], v[140:143], v[192:195], v[40:43]
	v_mfma_f32_16x16x32_bf16 v[32:35], v[132:135], v[206:209], v[32:35]
	v_mfma_f32_16x16x32_bf16 v[24:27], v[140:143], v[206:209], v[24:27]
	v_mfma_f32_16x16x32_bf16 v[16:19], v[132:135], v[214:217], v[16:19]
	v_mfma_f32_16x16x32_bf16 v[8:11], v[140:143], v[214:217], v[8:11]
	s_setprio 0
	s_setprio 1
	v_mfma_f32_16x16x32_bf16 v[52:55], v[144:147], v[160:163], v[52:55]
	v_mfma_f32_16x16x32_bf16 v[44:47], v[152:155], v[160:163], v[44:47]
	v_mfma_f32_16x16x32_bf16 v[36:39], v[144:147], v[188:191], v[36:39]
	v_mfma_f32_16x16x32_bf16 v[28:31], v[152:155], v[188:191], v[28:31]
	v_mfma_f32_16x16x32_bf16 v[20:23], v[144:147], v[202:205], v[20:23]
	v_mfma_f32_16x16x32_bf16 v[12:15], v[152:155], v[202:205], v[12:15]
	v_mfma_f32_16x16x32_bf16 v[4:7], v[144:147], v[210:213], v[4:7]
	v_mfma_f32_16x16x32_bf16 v[0:3], v[152:155], v[210:213], v[0:3]
	v_mfma_f32_16x16x32_bf16 v[52:55], v[148:151], v[164:167], v[52:55]
	v_mfma_f32_16x16x32_bf16 v[44:47], v[156:159], v[164:167], v[44:47]
	v_mfma_f32_16x16x32_bf16 v[36:39], v[148:151], v[192:195], v[36:39]
	v_mfma_f32_16x16x32_bf16 v[28:31], v[156:159], v[192:195], v[28:31]
	v_mfma_f32_16x16x32_bf16 v[20:23], v[148:151], v[206:209], v[20:23]
	v_mfma_f32_16x16x32_bf16 v[12:15], v[156:159], v[206:209], v[12:15]
	v_mfma_f32_16x16x32_bf16 v[4:7], v[148:151], v[214:217], v[4:7]
	v_mfma_f32_16x16x32_bf16 v[0:3], v[156:159], v[214:217], v[0:3]
	s_setprio 0
	s_barrier
	s_add_i32 s46, 0, 0x18000
	s_add_i32 s47, 0, 0x1c000
	v_add_u32_e32 v140, s46, v198
	v_add_u32_e32 v156, s47, v198
	ds_read_b128 v[128:131], v140
	ds_read_b128 v[132:135], v140 offset:1024
	ds_read_b128 v[136:139], v140 offset:2048
	ds_read_b128 v[140:143], v140 offset:3072
	ds_read_b128 v[144:147], v156
	ds_read_b128 v[148:151], v156 offset:1024
	ds_read_b128 v[152:155], v156 offset:2048
	ds_read_b128 v[156:159], v156 offset:3072
	s_add_u32 s22, s22, 0x100000
	s_addc_u32 s23, s23, 0
	s_mov_b32 m0, s31
	v_lshl_add_u64 v[224:225], s[22:23], 0, v[168:169]
	ds_read_b128 v[160:163], v201 offset:32768
	ds_read_b128 v[164:167], v201 offset:33792
	ds_read_b128 v[188:191], v201 offset:34816
	ds_read_b128 v[192:195], v201 offset:35840
	ds_read_b128 v[202:205], v201 offset:36864
	ds_read_b128 v[206:209], v201 offset:37888
	ds_read_b128 v[210:213], v201 offset:38912
	ds_read_b128 v[214:217], v201 offset:39936
	global_load_lds_dwordx4 v[224:225], off
	v_lshl_add_u64 v[224:225], s[22:23], 0, v[172:173]
	s_mov_b32 m0, s33
	s_nop 0
	global_load_lds_dwordx4 v[224:225], off
	s_waitcnt vmcnt(8)
	s_waitcnt lgkmcnt(0)
	s_barrier
	s_setprio 1
	s_waitcnt lgkmcnt(0)
	v_mfma_f32_16x16x32_bf16 v[124:127], v[128:131], v[160:163], v[124:127]
	v_mfma_f32_16x16x32_bf16 v[120:123], v[136:139], v[160:163], v[120:123]
	v_mfma_f32_16x16x32_bf16 v[112:115], v[128:131], v[188:191], v[112:115]
	v_mfma_f32_16x16x32_bf16 v[104:107], v[136:139], v[188:191], v[104:107]
	v_mfma_f32_16x16x32_bf16 v[96:99], v[128:131], v[202:205], v[96:99]
	v_mfma_f32_16x16x32_bf16 v[88:91], v[136:139], v[202:205], v[88:91]
	v_mfma_f32_16x16x32_bf16 v[80:83], v[128:131], v[210:213], v[80:83]
	v_mfma_f32_16x16x32_bf16 v[72:75], v[136:139], v[210:213], v[72:75]
	v_mfma_f32_16x16x32_bf16 v[124:127], v[132:135], v[164:167], v[124:127]
	v_mfma_f32_16x16x32_bf16 v[120:123], v[140:143], v[164:167], v[120:123]
	v_mfma_f32_16x16x32_bf16 v[112:115], v[132:135], v[192:195], v[112:115]
	v_mfma_f32_16x16x32_bf16 v[104:107], v[140:143], v[192:195], v[104:107]
	v_mfma_f32_16x16x32_bf16 v[96:99], v[132:135], v[206:209], v[96:99]
	v_mfma_f32_16x16x32_bf16 v[88:91], v[140:143], v[206:209], v[88:91]
	v_mfma_f32_16x16x32_bf16 v[80:83], v[132:135], v[214:217], v[80:83]
	v_mfma_f32_16x16x32_bf16 v[72:75], v[140:143], v[214:217], v[72:75]
	s_setprio 0
	s_setprio 1
	v_mfma_f32_16x16x32_bf16 v[116:119], v[144:147], v[160:163], v[116:119]
	v_mfma_f32_16x16x32_bf16 v[108:111], v[152:155], v[160:163], v[108:111]
	v_mfma_f32_16x16x32_bf16 v[100:103], v[144:147], v[188:191], v[100:103]
	v_mfma_f32_16x16x32_bf16 v[92:95], v[152:155], v[188:191], v[92:95]
	v_mfma_f32_16x16x32_bf16 v[84:87], v[144:147], v[202:205], v[84:87]
	v_mfma_f32_16x16x32_bf16 v[76:79], v[152:155], v[202:205], v[76:79]
	v_mfma_f32_16x16x32_bf16 v[68:71], v[144:147], v[210:213], v[68:71]
	v_mfma_f32_16x16x32_bf16 v[64:67], v[152:155], v[210:213], v[64:67]
	v_mfma_f32_16x16x32_bf16 v[116:119], v[148:151], v[164:167], v[116:119]
	v_mfma_f32_16x16x32_bf16 v[108:111], v[156:159], v[164:167], v[108:111]
	v_mfma_f32_16x16x32_bf16 v[100:103], v[148:151], v[192:195], v[100:103]
	v_mfma_f32_16x16x32_bf16 v[92:95], v[156:159], v[192:195], v[92:95]
	v_mfma_f32_16x16x32_bf16 v[84:87], v[148:151], v[206:209], v[84:87]
	v_mfma_f32_16x16x32_bf16 v[76:79], v[156:159], v[206:209], v[76:79]
	v_mfma_f32_16x16x32_bf16 v[68:71], v[148:151], v[214:217], v[68:71]
	v_mfma_f32_16x16x32_bf16 v[64:67], v[156:159], v[214:217], v[64:67]
	s_setprio 0
	s_barrier
; #define PG8_STAGE(bufoff, gbase, voff) do { _Pragma("unroll") for (int _i = 0; _i < 2; ++_i) \
;         __builtin_amdgcn_global_load_lds((const unsigned*)((const char*)(gbase) + (voff)[_i]), (PG8_LAS unsigned*)(lds + (bufoff) + ldsw + _i * 8192), 16, 0, 0); } while (0)
; #define PG8_LDA(dst, b, h) do { _Pragma("unroll") for (int m = 0; m < 4; ++m) _Pragma("unroll") for (int k = 0; k < 2; ++k) dst[m][k] = *(const PG8_LAS bf16x8*)(lds + PG8_SA(b, h) + aoff + m * 2048 + k * 1024); } while (0)
; #define PG8_MMA(ai, bj, At, Bt) do { __builtin_amdgcn_s_setprio(1); _Pragma("unroll") for (int m = 0; m < 4; ++m) _Pragma("unroll") for (int n = 0; n < 2; ++n) _Pragma("unroll") for (int k = 0; k < 2; ++k) \
;         acc[ai][bj][m][n] = __builtin_amdgcn_mfma_f32_16x16x32_bf16(Bt[n][k], At[m][k], acc[ai][bj][m][n], 0, 0, 0); __builtin_amdgcn_s_setprio(0); } while (0)
; #define PG8_WAIT_V(n) asm volatile("s_waitcnt vmcnt(" #n ")" ::: "memory")
; #define PG8_WAIT_L(n) asm volatile("s_waitcnt lgkmcnt(" #n ")" ::: "memory")
; #define PG8_BAR __builtin_amdgcn_s_barrier()
; #define PG8_SCHED __builtin_amdgcn_sched_barrier(0)
; template <class Epi, class Sched, bool ALIGN_EPI = false, bool SP2 = false>
; __device__ __forceinline__ void gemm_phase(PG8_LAS unsigned char* lds, const Gemm g, const Sched& S, const Epi& E) {
;     ...
;             PG8_WAIT_V(8); PG8_WAIT_L(0); PG8_BAR; PG8_MMA(0, 0, At, B0); PG8_MMA(0, 1, At, B1); PG8_BAR; PG8_SCHED;
;             PG8_LDA(At, 1, 1); PG8_STAGE(PG8_SB(1, 0), b3, voffB); PG8_STAGE(PG8_SB(1, 1), b3 + hstepB, voffB); PG8_STAGE(PG8_SA(1, 0), a3, voffA);
;             PG8_WAIT_V(8); PG8_WAIT_L(0); PG8_BAR; PG8_MMA(1, 0, At, B0); PG8_MMA(1, 1, At, B1); PG8_BAR; PG8_SCHED;
	s_add_i32 s22, s46, s29
	v_lshl_add_u64 v[196:197], v[196:197], 0, s[4:5]
	s_mov_b32 m0, s22
	ds_read_b128 v[160:163], v201 offset:49152
	ds_read_b128 v[164:167], v201 offset:50176
	ds_read_b128 v[188:191], v201 offset:51200
	ds_read_b128 v[192:195], v201 offset:52224
	ds_read_b128 v[202:205], v201 offset:53248
	ds_read_b128 v[206:209], v201 offset:54272
	ds_read_b128 v[210:213], v201 offset:55296
	ds_read_b128 v[214:217], v201 offset:56320
	global_load_lds_dwordx4 v[196:197], off
	s_add_i32 m0, s22, 0x2000
	s_add_u32 s20, s20, 0x100080
	v_lshl_add_u64 v[196:197], v[218:219], 0, s[4:5]
	s_addc_u32 s21, s21, 0
	s_add_i32 s22, s47, s29
	global_load_lds_dwordx4 v[196:197], off
	v_lshl_add_u64 v[196:197], s[20:21], 0, v[170:171]
	s_mov_b32 m0, s22
	s_nop 0
	global_load_lds_dwordx4 v[196:197], off
	v_lshl_add_u64 v[196:197], s[20:21], 0, v[174:175]
	s_add_i32 m0, s22, 0x2000
	s_nop 0
	global_load_lds_dwordx4 v[196:197], off
	v_lshl_add_u64 v[196:197], v[220:221], 0, s[4:5]
	s_mov_b32 m0, s35
	s_nop 0
	global_load_lds_dwordx4 v[196:197], off
	v_lshl_add_u64 v[196:197], v[222:223], 0, s[4:5]
	s_mov_b32 m0, s36
	s_nop 0
	global_load_lds_dwordx4 v[196:197], off
	s_waitcnt vmcnt(8)
	s_waitcnt lgkmcnt(0)
	s_barrier
	s_setprio 1
	s_waitcnt lgkmcnt(0)
	v_mfma_f32_16x16x32_bf16 v[60:63], v[128:131], v[160:163], v[60:63]
	v_mfma_f32_16x16x32_bf16 v[56:59], v[136:139], v[160:163], v[56:59]
	v_mfma_f32_16x16x32_bf16 v[48:51], v[128:131], v[188:191], v[48:51]
	v_mfma_f32_16x16x32_bf16 v[40:43], v[136:139], v[188:191], v[40:43]
	v_mfma_f32_16x16x32_bf16 v[32:35], v[128:131], v[202:205], v[32:35]
	v_mfma_f32_16x16x32_bf16 v[24:27], v[136:139], v[202:205], v[24:27]
	v_mfma_f32_16x16x32_bf16 v[16:19], v[128:131], v[210:213], v[16:19]
	v_mfma_f32_16x16x32_bf16 v[8:11], v[136:139], v[210:213], v[8:11]
	v_mfma_f32_16x16x32_bf16 v[60:63], v[132:135], v[164:167], v[60:63]
	v_mfma_f32_16x16x32_bf16 v[56:59], v[140:143], v[164:167], v[56:59]
	v_mfma_f32_16x16x32_bf16 v[48:51], v[132:135], v[192:195], v[48:51]
	v_mfma_f32_16x16x32_bf16 v[40:43], v[140:143], v[192:195], v[40:43]
	v_mfma_f32_16x16x32_bf16 v[32:35], v[132:135], v[206:209], v[32:35]
	v_mfma_f32_16x16x32_bf16 v[24:27], v[140:143], v[206:209], v[24:27]
	v_mfma_f32_16x16x32_bf16 v[16:19], v[132:135], v[214:217], v[16:19]
	v_mfma_f32_16x16x32_bf16 v[8:11], v[140:143], v[214:217], v[8:11]
	s_setprio 0
	s_setprio 1
	v_mfma_f32_16x16x32_bf16 v[52:55], v[144:147], v[160:163], v[52:55]
	v_mfma_f32_16x16x32_bf16 v[44:47], v[152:155], v[160:163], v[44:47]
	v_mfma_f32_16x16x32_bf16 v[36:39], v[144:147], v[188:191], v[36:39]
	v_mfma_f32_16x16x32_bf16 v[28:31], v[152:155], v[188:191], v[28:31]
	v_mfma_f32_16x16x32_bf16 v[20:23], v[144:147], v[202:205], v[20:23]
	v_mfma_f32_16x16x32_bf16 v[12:15], v[152:155], v[202:205], v[12:15]
	v_mfma_f32_16x16x32_bf16 v[4:7], v[144:147], v[210:213], v[4:7]
	v_mfma_f32_16x16x32_bf16 v[0:3], v[152:155], v[210:213], v[0:3]
	v_mfma_f32_16x16x32_bf16 v[52:55], v[148:151], v[164:167], v[52:55]
	v_mfma_f32_16x16x32_bf16 v[44:47], v[156:159], v[164:167], v[44:47]
	v_mfma_f32_16x16x32_bf16 v[36:39], v[148:151], v[192:195], v[36:39]
	v_mfma_f32_16x16x32_bf16 v[28:31], v[156:159], v[192:195], v[28:31]
	v_mfma_f32_16x16x32_bf16 v[20:23], v[148:151], v[206:209], v[20:23]
	v_mfma_f32_16x16x32_bf16 v[12:15], v[156:159], v[206:209], v[12:15]
	v_mfma_f32_16x16x32_bf16 v[4:7], v[148:151], v[214:217], v[4:7]
	v_mfma_f32_16x16x32_bf16 v[0:3], v[156:159], v[214:217], v[0:3]
	s_setprio 0
	s_add_i32 s45, s45, 2
	s_add_u32 s18, s18, 0x100
	s_addc_u32 s19, s19, 0
	s_add_u32 s43, s43, 0x100
	s_addc_u32 s44, s44, 0
	s_cmp_gt_u32 s45, 61
	s_barrier
	s_cbranch_scc0 .LBB0_1061
	s_and_b64 vcc, exec, s[6:7]
	s_cbranch_vccz .LBB0_1064
	s_barrier
